# GEMM k-loops: counter/pointer increments and exit compare moved in front of the loop-back barrier (back-edge rotation)
# baseline (speedup 1.0000x reference)
.LBB0_229:
	s_add_u32 s16, s0, 0xfffc0080
	s_addc_u32 s17, s1, -1
	s_add_i32 s60, 0, 0x10000
	s_cmp_eq_u32 s59, 12
	s_cselect_b32 s19, s11, s17
	s_cselect_b32 s18, s55, s16
	s_cselect_b32 s17, s9, s58
	s_cselect_b32 s16, s56, s57
	s_add_i32 s62, 0, 0x14000
	v_add_u32_e32 v152, s60, v167
	v_add_u32_e32 v164, s62, v167
	ds_read_b128 v[140:143], v152
	ds_read_b128 v[144:147], v152 offset:1024
	ds_read_b128 v[148:151], v152 offset:2048
	ds_read_b128 v[152:155], v152 offset:3072
	ds_read_b128 v[156:159], v164
	ds_read_b128 v[160:163], v164 offset:1024
	ds_read_b128 v[190:193], v164 offset:2048
	ds_read_b128 v[198:201], v164 offset:3072
	v_lshl_add_u64 v[178:179], s[0:1], 0, v[136:137]
	s_add_i32 m0, s23, 0xc000
	ds_read_b128 v[202:205], v197
	ds_read_b128 v[206:209], v197 offset:1024
	ds_read_b128 v[220:223], v197 offset:2048
	ds_read_b128 v[224:227], v197 offset:3072
	ds_read_b128 v[228:231], v197 offset:4096
	ds_read_b128 v[232:235], v197 offset:5120
	ds_read_b128 v[236:239], v197 offset:6144
	ds_read_b128 v[240:243], v197 offset:7168
	global_load_lds_dwordx4 v[178:179], off
	v_lshl_add_u64 v[178:179], s[0:1], 0, v[138:139]
	s_add_i32 m0, s23, 0xe000
	s_nop 0
	global_load_lds_dwordx4 v[178:179], off
	s_waitcnt vmcnt(8)
	s_waitcnt lgkmcnt(0)
	s_barrier
	s_setprio 1
	s_waitcnt lgkmcnt(0)
	v_mfma_f32_16x16x32_bf16 v[124:127], v[140:143], v[202:205], v[124:127]
	v_mfma_f32_16x16x32_bf16 v[120:123], v[148:151], v[202:205], v[120:123]
	v_mfma_f32_16x16x32_bf16 v[112:115], v[140:143], v[220:223], v[112:115]
	v_mfma_f32_16x16x32_bf16 v[104:107], v[148:151], v[220:223], v[104:107]
	v_mfma_f32_16x16x32_bf16 v[96:99], v[140:143], v[228:231], v[96:99]
	v_mfma_f32_16x16x32_bf16 v[88:91], v[148:151], v[228:231], v[88:91]
	v_mfma_f32_16x16x32_bf16 v[80:83], v[140:143], v[236:239], v[80:83]
	v_mfma_f32_16x16x32_bf16 v[72:75], v[148:151], v[236:239], v[72:75]
	v_mfma_f32_16x16x32_bf16 v[124:127], v[144:147], v[206:209], v[124:127]
	v_mfma_f32_16x16x32_bf16 v[120:123], v[152:155], v[206:209], v[120:123]
	v_mfma_f32_16x16x32_bf16 v[112:115], v[144:147], v[224:227], v[112:115]
	v_mfma_f32_16x16x32_bf16 v[104:107], v[152:155], v[224:227], v[104:107]
	v_mfma_f32_16x16x32_bf16 v[96:99], v[144:147], v[232:235], v[96:99]
	v_mfma_f32_16x16x32_bf16 v[88:91], v[152:155], v[232:235], v[88:91]
	v_mfma_f32_16x16x32_bf16 v[80:83], v[144:147], v[240:243], v[80:83]
	v_mfma_f32_16x16x32_bf16 v[72:75], v[152:155], v[240:243], v[72:75]
	s_setprio 0
	s_setprio 1
	v_mfma_f32_16x16x32_bf16 v[116:119], v[156:159], v[202:205], v[116:119]
	v_mfma_f32_16x16x32_bf16 v[108:111], v[190:193], v[202:205], v[108:111]
	v_mfma_f32_16x16x32_bf16 v[100:103], v[156:159], v[220:223], v[100:103]
	v_mfma_f32_16x16x32_bf16 v[92:95], v[190:193], v[220:223], v[92:95]
	v_mfma_f32_16x16x32_bf16 v[84:87], v[156:159], v[228:231], v[84:87]
	v_mfma_f32_16x16x32_bf16 v[76:79], v[190:193], v[228:231], v[76:79]
	v_mfma_f32_16x16x32_bf16 v[68:71], v[156:159], v[236:239], v[68:71]
	v_mfma_f32_16x16x32_bf16 v[64:67], v[190:193], v[236:239], v[64:67]
	v_mfma_f32_16x16x32_bf16 v[116:119], v[160:163], v[206:209], v[116:119]
	v_mfma_f32_16x16x32_bf16 v[108:111], v[198:201], v[206:209], v[108:111]
	v_mfma_f32_16x16x32_bf16 v[100:103], v[160:163], v[224:227], v[100:103]
	v_mfma_f32_16x16x32_bf16 v[92:95], v[198:201], v[224:227], v[92:95]
	v_mfma_f32_16x16x32_bf16 v[84:87], v[160:163], v[232:235], v[84:87]
	v_mfma_f32_16x16x32_bf16 v[76:79], v[198:201], v[232:235], v[76:79]
	v_mfma_f32_16x16x32_bf16 v[68:71], v[160:163], v[240:243], v[68:71]
	v_mfma_f32_16x16x32_bf16 v[64:67], v[198:201], v[240:243], v[64:67]
	s_setprio 0
	s_barrier
	s_add_i32 s60, s60, s22
	v_lshl_add_u64 v[178:179], s[16:17], 0, v[168:169]
	s_mov_b32 m0, s60
	ds_read_b128 v[202:205], v197 offset:16384
	ds_read_b128 v[206:209], v197 offset:17408
	ds_read_b128 v[220:223], v197 offset:18432
	ds_read_b128 v[224:227], v197 offset:19456
	ds_read_b128 v[228:231], v197 offset:20480
	ds_read_b128 v[232:235], v197 offset:21504
	ds_read_b128 v[236:239], v197 offset:22528
	ds_read_b128 v[240:243], v197 offset:23552
	global_load_lds_dwordx4 v[178:179], off
	s_add_i32 m0, s60, 0x2000
	s_add_u32 s60, s16, 0x40000
	v_lshl_add_u64 v[180:181], s[16:17], 0, v[128:129]
	s_addc_u32 s61, s17, 0
	s_add_i32 s62, s62, s22
	global_load_lds_dwordx4 v[180:181], off
	v_lshl_add_u64 v[194:195], s[60:61], 0, v[168:169]
	s_mov_b32 m0, s62
	v_lshl_add_u64 v[244:245], s[18:19], 0, v[130:131]
	global_load_lds_dwordx4 v[194:195], off
	v_lshl_add_u64 v[194:195], s[60:61], 0, v[128:129]
	s_add_i32 m0, s62, 0x2000
	s_nop 0
	global_load_lds_dwordx4 v[194:195], off
	v_lshl_add_u64 v[194:195], s[18:19], 0, v[132:133]
	s_mov_b32 m0, s23
	s_nop 0
	global_load_lds_dwordx4 v[194:195], off
	s_mov_b32 m0, s24
	s_nop 0
	global_load_lds_dwordx4 v[244:245], off
	s_waitcnt vmcnt(8)
	s_waitcnt lgkmcnt(0)
	s_barrier
	s_setprio 1
	s_waitcnt lgkmcnt(0)
	v_mfma_f32_16x16x32_bf16 v[60:63], v[140:143], v[202:205], v[60:63]
	v_mfma_f32_16x16x32_bf16 v[56:59], v[148:151], v[202:205], v[56:59]
	v_mfma_f32_16x16x32_bf16 v[48:51], v[140:143], v[220:223], v[48:51]
	v_mfma_f32_16x16x32_bf16 v[40:43], v[148:151], v[220:223], v[40:43]
	v_mfma_f32_16x16x32_bf16 v[32:35], v[140:143], v[228:231], v[32:35]
	v_mfma_f32_16x16x32_bf16 v[24:27], v[148:151], v[228:231], v[24:27]
	v_mfma_f32_16x16x32_bf16 v[16:19], v[140:143], v[236:239], v[16:19]
	v_mfma_f32_16x16x32_bf16 v[8:11], v[148:151], v[236:239], v[8:11]
	v_mfma_f32_16x16x32_bf16 v[60:63], v[144:147], v[206:209], v[60:63]
	v_mfma_f32_16x16x32_bf16 v[56:59], v[152:155], v[206:209], v[56:59]
	v_mfma_f32_16x16x32_bf16 v[48:51], v[144:147], v[224:227], v[48:51]
	v_mfma_f32_16x16x32_bf16 v[40:43], v[152:155], v[224:227], v[40:43]
	v_mfma_f32_16x16x32_bf16 v[32:35], v[144:147], v[232:235], v[32:35]
	v_mfma_f32_16x16x32_bf16 v[24:27], v[152:155], v[232:235], v[24:27]
	v_mfma_f32_16x16x32_bf16 v[16:19], v[144:147], v[240:243], v[16:19]
	v_mfma_f32_16x16x32_bf16 v[8:11], v[152:155], v[240:243], v[8:11]
	s_setprio 0
	s_setprio 1
	v_mfma_f32_16x16x32_bf16 v[52:55], v[156:159], v[202:205], v[52:55]
	v_mfma_f32_16x16x32_bf16 v[44:47], v[190:193], v[202:205], v[44:47]
	v_mfma_f32_16x16x32_bf16 v[36:39], v[156:159], v[220:223], v[36:39]
	v_mfma_f32_16x16x32_bf16 v[28:31], v[190:193], v[220:223], v[28:31]
	v_mfma_f32_16x16x32_bf16 v[20:23], v[156:159], v[228:231], v[20:23]
	v_mfma_f32_16x16x32_bf16 v[12:15], v[190:193], v[228:231], v[12:15]
	v_mfma_f32_16x16x32_bf16 v[4:7], v[156:159], v[236:239], v[4:7]
	v_mfma_f32_16x16x32_bf16 v[0:3], v[190:193], v[236:239], v[0:3]
	v_mfma_f32_16x16x32_bf16 v[52:55], v[160:163], v[206:209], v[52:55]
	v_mfma_f32_16x16x32_bf16 v[44:47], v[198:201], v[206:209], v[44:47]
	v_mfma_f32_16x16x32_bf16 v[36:39], v[160:163], v[224:227], v[36:39]
	v_mfma_f32_16x16x32_bf16 v[28:31], v[198:201], v[224:227], v[28:31]
	v_mfma_f32_16x16x32_bf16 v[20:23], v[160:163], v[232:235], v[20:23]
	v_mfma_f32_16x16x32_bf16 v[12:15], v[198:201], v[232:235], v[12:15]
	v_mfma_f32_16x16x32_bf16 v[4:7], v[160:163], v[240:243], v[4:7]
	v_mfma_f32_16x16x32_bf16 v[0:3], v[198:201], v[240:243], v[0:3]
	s_setprio 0
	s_barrier
	s_add_i32 s60, 0, 0x18000
	s_add_i32 s61, 0, 0x1c000
	v_add_u32_e32 v152, s60, v167
	v_add_u32_e32 v164, s61, v167
	ds_read_b128 v[140:143], v152
	ds_read_b128 v[144:147], v152 offset:1024
	ds_read_b128 v[148:151], v152 offset:2048
	ds_read_b128 v[152:155], v152 offset:3072
	ds_read_b128 v[156:159], v164
	ds_read_b128 v[160:163], v164 offset:1024
	ds_read_b128 v[190:193], v164 offset:2048
	ds_read_b128 v[198:201], v164 offset:3072
	s_add_u32 s18, s18, 0x40000
	s_addc_u32 s19, s19, 0
	s_mov_b32 m0, s25
	v_lshl_add_u64 v[246:247], s[18:19], 0, v[132:133]
	ds_read_b128 v[202:205], v197 offset:32768
	ds_read_b128 v[206:209], v197 offset:33792
	ds_read_b128 v[220:223], v197 offset:34816
	ds_read_b128 v[224:227], v197 offset:35840
	ds_read_b128 v[228:231], v197 offset:36864
	ds_read_b128 v[232:235], v197 offset:37888
	ds_read_b128 v[236:239], v197 offset:38912
	ds_read_b128 v[240:243], v197 offset:39936
	global_load_lds_dwordx4 v[246:247], off
	v_lshl_add_u64 v[246:247], s[18:19], 0, v[130:131]
	s_mov_b32 m0, s26
	s_nop 0
	global_load_lds_dwordx4 v[246:247], off
	s_waitcnt vmcnt(8)
	s_waitcnt lgkmcnt(0)
	s_barrier
	s_setprio 1
	s_waitcnt lgkmcnt(0)
	v_mfma_f32_16x16x32_bf16 v[124:127], v[140:143], v[202:205], v[124:127]
	v_mfma_f32_16x16x32_bf16 v[120:123], v[148:151], v[202:205], v[120:123]
	v_mfma_f32_16x16x32_bf16 v[112:115], v[140:143], v[220:223], v[112:115]
	v_mfma_f32_16x16x32_bf16 v[104:107], v[148:151], v[220:223], v[104:107]
	v_mfma_f32_16x16x32_bf16 v[96:99], v[140:143], v[228:231], v[96:99]
	v_mfma_f32_16x16x32_bf16 v[88:91], v[148:151], v[228:231], v[88:91]
	v_mfma_f32_16x16x32_bf16 v[80:83], v[140:143], v[236:239], v[80:83]
	v_mfma_f32_16x16x32_bf16 v[72:75], v[148:151], v[236:239], v[72:75]
	v_mfma_f32_16x16x32_bf16 v[124:127], v[144:147], v[206:209], v[124:127]
	v_mfma_f32_16x16x32_bf16 v[120:123], v[152:155], v[206:209], v[120:123]
	v_mfma_f32_16x16x32_bf16 v[112:115], v[144:147], v[224:227], v[112:115]
	v_mfma_f32_16x16x32_bf16 v[104:107], v[152:155], v[224:227], v[104:107]
	v_mfma_f32_16x16x32_bf16 v[96:99], v[144:147], v[232:235], v[96:99]
	v_mfma_f32_16x16x32_bf16 v[88:91], v[152:155], v[232:235], v[88:91]
	v_mfma_f32_16x16x32_bf16 v[80:83], v[144:147], v[240:243], v[80:83]
	v_mfma_f32_16x16x32_bf16 v[72:75], v[152:155], v[240:243], v[72:75]
	s_setprio 0
	s_setprio 1
	v_mfma_f32_16x16x32_bf16 v[116:119], v[156:159], v[202:205], v[116:119]
	v_mfma_f32_16x16x32_bf16 v[108:111], v[190:193], v[202:205], v[108:111]
	v_mfma_f32_16x16x32_bf16 v[100:103], v[156:159], v[220:223], v[100:103]
	v_mfma_f32_16x16x32_bf16 v[92:95], v[190:193], v[220:223], v[92:95]
	v_mfma_f32_16x16x32_bf16 v[84:87], v[156:159], v[228:231], v[84:87]
	v_mfma_f32_16x16x32_bf16 v[76:79], v[190:193], v[228:231], v[76:79]
	v_mfma_f32_16x16x32_bf16 v[68:71], v[156:159], v[236:239], v[68:71]
	v_mfma_f32_16x16x32_bf16 v[64:67], v[190:193], v[236:239], v[64:67]
	v_mfma_f32_16x16x32_bf16 v[116:119], v[160:163], v[206:209], v[116:119]
	v_mfma_f32_16x16x32_bf16 v[108:111], v[198:201], v[206:209], v[108:111]
	v_mfma_f32_16x16x32_bf16 v[100:103], v[160:163], v[224:227], v[100:103]
	v_mfma_f32_16x16x32_bf16 v[92:95], v[198:201], v[224:227], v[92:95]
	v_mfma_f32_16x16x32_bf16 v[84:87], v[160:163], v[232:235], v[84:87]
	v_mfma_f32_16x16x32_bf16 v[76:79], v[198:201], v[232:235], v[76:79]
	v_mfma_f32_16x16x32_bf16 v[68:71], v[160:163], v[240:243], v[68:71]
	v_mfma_f32_16x16x32_bf16 v[64:67], v[198:201], v[240:243], v[64:67]
	s_setprio 0
	s_barrier
	s_add_i32 s18, s60, s22
	v_lshl_add_u64 v[178:179], v[178:179], 0, s[50:51]
	s_mov_b32 m0, s18
	ds_read_b128 v[202:205], v197 offset:49152
	ds_read_b128 v[206:209], v197 offset:50176
	ds_read_b128 v[220:223], v197 offset:51200
	ds_read_b128 v[224:227], v197 offset:52224
	ds_read_b128 v[228:231], v197 offset:53248
	ds_read_b128 v[232:235], v197 offset:54272
	ds_read_b128 v[236:239], v197 offset:55296
	ds_read_b128 v[240:243], v197 offset:56320
	global_load_lds_dwordx4 v[178:179], off
	s_add_i32 m0, s18, 0x2000
	s_add_u32 s16, s16, 0x40080
	v_lshl_add_u64 v[178:179], v[180:181], 0, s[50:51]
	s_addc_u32 s17, s17, 0
	s_add_i32 s18, s61, s22
	global_load_lds_dwordx4 v[178:179], off
	v_lshl_add_u64 v[178:179], s[16:17], 0, v[168:169]
	s_mov_b32 m0, s18
	s_nop 0
	global_load_lds_dwordx4 v[178:179], off
	v_lshl_add_u64 v[178:179], s[16:17], 0, v[128:129]
	s_add_i32 m0, s18, 0x2000
	s_nop 0
	global_load_lds_dwordx4 v[178:179], off
	v_lshl_add_u64 v[178:179], v[194:195], 0, s[50:51]
	s_mov_b32 m0, s27
	s_nop 0
	global_load_lds_dwordx4 v[178:179], off
	v_lshl_add_u64 v[178:179], v[244:245], 0, s[50:51]
	s_mov_b32 m0, s34
	s_nop 0
	global_load_lds_dwordx4 v[178:179], off
	s_waitcnt vmcnt(8)
	s_waitcnt lgkmcnt(0)
	s_barrier
	s_setprio 1
	s_waitcnt lgkmcnt(0)
	v_mfma_f32_16x16x32_bf16 v[60:63], v[140:143], v[202:205], v[60:63]
	v_mfma_f32_16x16x32_bf16 v[56:59], v[148:151], v[202:205], v[56:59]
	v_mfma_f32_16x16x32_bf16 v[48:51], v[140:143], v[220:223], v[48:51]
	v_mfma_f32_16x16x32_bf16 v[40:43], v[148:151], v[220:223], v[40:43]
	v_mfma_f32_16x16x32_bf16 v[32:35], v[140:143], v[228:231], v[32:35]
	v_mfma_f32_16x16x32_bf16 v[24:27], v[148:151], v[228:231], v[24:27]
	v_mfma_f32_16x16x32_bf16 v[16:19], v[140:143], v[236:239], v[16:19]
	v_mfma_f32_16x16x32_bf16 v[8:11], v[148:151], v[236:239], v[8:11]
	v_mfma_f32_16x16x32_bf16 v[60:63], v[144:147], v[206:209], v[60:63]
	v_mfma_f32_16x16x32_bf16 v[56:59], v[152:155], v[206:209], v[56:59]
	v_mfma_f32_16x16x32_bf16 v[48:51], v[144:147], v[224:227], v[48:51]
	v_mfma_f32_16x16x32_bf16 v[40:43], v[152:155], v[224:227], v[40:43]
	v_mfma_f32_16x16x32_bf16 v[32:35], v[144:147], v[232:235], v[32:35]
	v_mfma_f32_16x16x32_bf16 v[24:27], v[152:155], v[232:235], v[24:27]
	v_mfma_f32_16x16x32_bf16 v[16:19], v[144:147], v[240:243], v[16:19]
	v_mfma_f32_16x16x32_bf16 v[8:11], v[152:155], v[240:243], v[8:11]
	s_setprio 0
	s_setprio 1
	v_mfma_f32_16x16x32_bf16 v[52:55], v[156:159], v[202:205], v[52:55]
	v_mfma_f32_16x16x32_bf16 v[44:47], v[190:193], v[202:205], v[44:47]
	v_mfma_f32_16x16x32_bf16 v[36:39], v[156:159], v[220:223], v[36:39]
	v_mfma_f32_16x16x32_bf16 v[28:31], v[190:193], v[220:223], v[28:31]
	v_mfma_f32_16x16x32_bf16 v[20:23], v[156:159], v[228:231], v[20:23]
	v_mfma_f32_16x16x32_bf16 v[12:15], v[190:193], v[228:231], v[12:15]
	v_mfma_f32_16x16x32_bf16 v[4:7], v[156:159], v[236:239], v[4:7]
	v_mfma_f32_16x16x32_bf16 v[0:3], v[190:193], v[236:239], v[0:3]
	v_mfma_f32_16x16x32_bf16 v[52:55], v[160:163], v[206:209], v[52:55]
	v_mfma_f32_16x16x32_bf16 v[44:47], v[198:201], v[206:209], v[44:47]
	v_mfma_f32_16x16x32_bf16 v[36:39], v[160:163], v[224:227], v[36:39]
	v_mfma_f32_16x16x32_bf16 v[28:31], v[198:201], v[224:227], v[28:31]
	v_mfma_f32_16x16x32_bf16 v[20:23], v[160:163], v[232:235], v[20:23]
	v_mfma_f32_16x16x32_bf16 v[12:15], v[198:201], v[232:235], v[12:15]
	v_mfma_f32_16x16x32_bf16 v[4:7], v[160:163], v[240:243], v[4:7]
	v_mfma_f32_16x16x32_bf16 v[0:3], v[198:201], v[240:243], v[0:3]
	s_add_i32 s59, s59, 2
	s_add_u32 s0, s0, 0x100
	s_addc_u32 s1, s1, 0
	s_add_u32 s57, s57, 0x100
	s_addc_u32 s58, s58, 0
	s_cmp_gt_u32 s59, 13
	s_setprio 0
	s_barrier
	s_cbranch_scc0 .LBB0_229
	s_and_b64 vcc, exec, s[6:7]
	s_cbranch_vccz .LBB0_232
	s_barrier

.LBB0_411:
	s_add_u32 s18, s16, 0xfffc0080
	s_addc_u32 s19, s17, -1
	s_add_i32 s60, 0, 0x10000
	s_cmp_eq_u32 s90, 12
	s_cselect_b32 s21, s11, s19
	s_cselect_b32 s20, s56, s18
	s_cselect_b32 s19, s9, s59
	s_cselect_b32 s18, s57, s58
	s_add_i32 s62, 0, 0x14000
	v_add_u32_e32 v136, s60, v196
	v_add_u32_e32 v166, s62, v196
	ds_read_b128 v[120:123], v136
	ds_read_b128 v[124:127], v136 offset:1024
	ds_read_b128 v[128:131], v136 offset:2048
	ds_read_b128 v[136:139], v136 offset:3072
	ds_read_b128 v[144:147], v166
	ds_read_b128 v[158:161], v166 offset:1024
	ds_read_b128 v[162:165], v166 offset:2048
	ds_read_b128 v[190:193], v166 offset:3072
	v_lshl_add_u64 v[166:167], s[16:17], 0, v[154:155]
	s_add_i32 m0, s25, 0xc000
	ds_read_b128 v[200:203], v198
	ds_read_b128 v[204:207], v198 offset:1024
	ds_read_b128 v[220:223], v198 offset:2048
	ds_read_b128 v[224:227], v198 offset:3072
	ds_read_b128 v[228:231], v198 offset:4096
	ds_read_b128 v[232:235], v198 offset:5120
	ds_read_b128 v[236:239], v198 offset:6144
	ds_read_b128 v[240:243], v198 offset:7168
	global_load_lds_dwordx4 v[166:167], off
	v_lshl_add_u64 v[166:167], s[16:17], 0, v[156:157]
	s_add_i32 m0, s25, 0xe000
	s_nop 0
	global_load_lds_dwordx4 v[166:167], off
	s_waitcnt vmcnt(8)
	s_waitcnt lgkmcnt(0)
	s_barrier
	s_setprio 1
	s_waitcnt lgkmcnt(0)
	v_mfma_f32_16x16x32_bf16 v[140:143], v[120:123], v[200:203], v[140:143]
	v_mfma_f32_16x16x32_bf16 v[132:135], v[128:131], v[200:203], v[132:135]
	v_mfma_f32_16x16x32_bf16 v[108:111], v[120:123], v[220:223], v[108:111]
	v_mfma_f32_16x16x32_bf16 v[104:107], v[128:131], v[220:223], v[104:107]
	v_mfma_f32_16x16x32_bf16 v[92:95], v[120:123], v[228:231], v[92:95]
	v_mfma_f32_16x16x32_bf16 v[88:91], v[128:131], v[228:231], v[88:91]
	v_mfma_f32_16x16x32_bf16 v[76:79], v[120:123], v[236:239], v[76:79]
	v_mfma_f32_16x16x32_bf16 v[72:75], v[128:131], v[236:239], v[72:75]
	v_mfma_f32_16x16x32_bf16 v[140:143], v[124:127], v[204:207], v[140:143]
	v_mfma_f32_16x16x32_bf16 v[132:135], v[136:139], v[204:207], v[132:135]
	v_mfma_f32_16x16x32_bf16 v[108:111], v[124:127], v[224:227], v[108:111]
	v_mfma_f32_16x16x32_bf16 v[104:107], v[136:139], v[224:227], v[104:107]
	v_mfma_f32_16x16x32_bf16 v[92:95], v[124:127], v[232:235], v[92:95]
	v_mfma_f32_16x16x32_bf16 v[88:91], v[136:139], v[232:235], v[88:91]
	v_mfma_f32_16x16x32_bf16 v[76:79], v[124:127], v[240:243], v[76:79]
	v_mfma_f32_16x16x32_bf16 v[72:75], v[136:139], v[240:243], v[72:75]
	s_setprio 0
	s_setprio 1
	v_mfma_f32_16x16x32_bf16 v[116:119], v[144:147], v[200:203], v[116:119]
	v_mfma_f32_16x16x32_bf16 v[112:115], v[162:165], v[200:203], v[112:115]
	v_mfma_f32_16x16x32_bf16 v[100:103], v[144:147], v[220:223], v[100:103]
	v_mfma_f32_16x16x32_bf16 v[96:99], v[162:165], v[220:223], v[96:99]
	v_mfma_f32_16x16x32_bf16 v[84:87], v[144:147], v[228:231], v[84:87]
	v_mfma_f32_16x16x32_bf16 v[80:83], v[162:165], v[228:231], v[80:83]
	v_mfma_f32_16x16x32_bf16 v[68:71], v[144:147], v[236:239], v[68:71]
	v_mfma_f32_16x16x32_bf16 v[64:67], v[162:165], v[236:239], v[64:67]
	v_mfma_f32_16x16x32_bf16 v[116:119], v[158:161], v[204:207], v[116:119]
	v_mfma_f32_16x16x32_bf16 v[112:115], v[190:193], v[204:207], v[112:115]
	v_mfma_f32_16x16x32_bf16 v[100:103], v[158:161], v[224:227], v[100:103]
	v_mfma_f32_16x16x32_bf16 v[96:99], v[190:193], v[224:227], v[96:99]
	v_mfma_f32_16x16x32_bf16 v[84:87], v[158:161], v[232:235], v[84:87]
	v_mfma_f32_16x16x32_bf16 v[80:83], v[190:193], v[232:235], v[80:83]
	v_mfma_f32_16x16x32_bf16 v[68:71], v[158:161], v[240:243], v[68:71]
	v_mfma_f32_16x16x32_bf16 v[64:67], v[190:193], v[240:243], v[64:67]
	s_setprio 0
	s_barrier
	s_add_i32 s60, s60, s24
	v_lshl_add_u64 v[166:167], s[18:19], 0, v[168:169]
	s_mov_b32 m0, s60
	ds_read_b128 v[200:203], v198 offset:16384
	ds_read_b128 v[204:207], v198 offset:17408
	ds_read_b128 v[220:223], v198 offset:18432
	ds_read_b128 v[224:227], v198 offset:19456
	ds_read_b128 v[228:231], v198 offset:20480
	ds_read_b128 v[232:235], v198 offset:21504
	ds_read_b128 v[236:239], v198 offset:22528
	ds_read_b128 v[240:243], v198 offset:23552
	global_load_lds_dwordx4 v[166:167], off
	s_add_i32 m0, s60, 0x2000
	s_add_u32 s60, s18, 0x40000
	v_lshl_add_u64 v[178:179], s[18:19], 0, v[148:149]
	s_addc_u32 s61, s19, 0
	s_add_i32 s62, s62, s24
	global_load_lds_dwordx4 v[178:179], off
	v_lshl_add_u64 v[180:181], s[60:61], 0, v[168:169]
	s_mov_b32 m0, s62
	v_lshl_add_u64 v[194:195], s[20:21], 0, v[150:151]
	global_load_lds_dwordx4 v[180:181], off
	v_lshl_add_u64 v[180:181], s[60:61], 0, v[148:149]
	s_add_i32 m0, s62, 0x2000
	s_nop 0
	global_load_lds_dwordx4 v[180:181], off
	v_lshl_add_u64 v[180:181], s[20:21], 0, v[152:153]
	s_mov_b32 m0, s25
	s_nop 0
	global_load_lds_dwordx4 v[180:181], off
	s_mov_b32 m0, s26
	s_nop 0
	global_load_lds_dwordx4 v[194:195], off
	s_waitcnt vmcnt(8)
	s_waitcnt lgkmcnt(0)
	s_barrier
	s_setprio 1
	s_waitcnt lgkmcnt(0)
	v_mfma_f32_16x16x32_bf16 v[60:63], v[120:123], v[200:203], v[60:63]
	v_mfma_f32_16x16x32_bf16 v[56:59], v[128:131], v[200:203], v[56:59]
	v_mfma_f32_16x16x32_bf16 v[44:47], v[120:123], v[220:223], v[44:47]
	v_mfma_f32_16x16x32_bf16 v[40:43], v[128:131], v[220:223], v[40:43]
	v_mfma_f32_16x16x32_bf16 v[28:31], v[120:123], v[228:231], v[28:31]
	v_mfma_f32_16x16x32_bf16 v[24:27], v[128:131], v[228:231], v[24:27]
	v_mfma_f32_16x16x32_bf16 v[12:15], v[120:123], v[236:239], v[12:15]
	v_mfma_f32_16x16x32_bf16 v[8:11], v[128:131], v[236:239], v[8:11]
	v_mfma_f32_16x16x32_bf16 v[60:63], v[124:127], v[204:207], v[60:63]
	v_mfma_f32_16x16x32_bf16 v[56:59], v[136:139], v[204:207], v[56:59]
	v_mfma_f32_16x16x32_bf16 v[44:47], v[124:127], v[224:227], v[44:47]
	v_mfma_f32_16x16x32_bf16 v[40:43], v[136:139], v[224:227], v[40:43]
	v_mfma_f32_16x16x32_bf16 v[28:31], v[124:127], v[232:235], v[28:31]
	v_mfma_f32_16x16x32_bf16 v[24:27], v[136:139], v[232:235], v[24:27]
	v_mfma_f32_16x16x32_bf16 v[12:15], v[124:127], v[240:243], v[12:15]
	v_mfma_f32_16x16x32_bf16 v[8:11], v[136:139], v[240:243], v[8:11]
	s_setprio 0
	s_setprio 1
	v_mfma_f32_16x16x32_bf16 v[52:55], v[144:147], v[200:203], v[52:55]
	v_mfma_f32_16x16x32_bf16 v[48:51], v[162:165], v[200:203], v[48:51]
	v_mfma_f32_16x16x32_bf16 v[36:39], v[144:147], v[220:223], v[36:39]
	v_mfma_f32_16x16x32_bf16 v[32:35], v[162:165], v[220:223], v[32:35]
	v_mfma_f32_16x16x32_bf16 v[20:23], v[144:147], v[228:231], v[20:23]
	v_mfma_f32_16x16x32_bf16 v[16:19], v[162:165], v[228:231], v[16:19]
	v_mfma_f32_16x16x32_bf16 v[4:7], v[144:147], v[236:239], v[4:7]
	v_mfma_f32_16x16x32_bf16 v[0:3], v[162:165], v[236:239], v[0:3]
	v_mfma_f32_16x16x32_bf16 v[52:55], v[158:161], v[204:207], v[52:55]
	v_mfma_f32_16x16x32_bf16 v[48:51], v[190:193], v[204:207], v[48:51]
	v_mfma_f32_16x16x32_bf16 v[36:39], v[158:161], v[224:227], v[36:39]
	v_mfma_f32_16x16x32_bf16 v[32:35], v[190:193], v[224:227], v[32:35]
	v_mfma_f32_16x16x32_bf16 v[20:23], v[158:161], v[232:235], v[20:23]
	v_mfma_f32_16x16x32_bf16 v[16:19], v[190:193], v[232:235], v[16:19]
	v_mfma_f32_16x16x32_bf16 v[4:7], v[158:161], v[240:243], v[4:7]
	v_mfma_f32_16x16x32_bf16 v[0:3], v[190:193], v[240:243], v[0:3]
	s_setprio 0
	s_barrier
	s_add_i32 s60, 0, 0x18000
	s_add_i32 s61, 0, 0x1c000
	v_add_u32_e32 v136, s60, v196
	v_add_u32_e32 v190, s61, v196
	ds_read_b128 v[120:123], v136
	ds_read_b128 v[124:127], v136 offset:1024
	ds_read_b128 v[128:131], v136 offset:2048
	ds_read_b128 v[136:139], v136 offset:3072
	ds_read_b128 v[144:147], v190
	ds_read_b128 v[158:161], v190 offset:1024
	ds_read_b128 v[162:165], v190 offset:2048
	ds_read_b128 v[190:193], v190 offset:3072
	s_add_u32 s20, s20, 0x40000
	s_addc_u32 s21, s21, 0
	s_mov_b32 m0, s27
	v_lshl_add_u64 v[208:209], s[20:21], 0, v[152:153]
	ds_read_b128 v[200:203], v198 offset:32768
	ds_read_b128 v[204:207], v198 offset:33792
	ds_read_b128 v[220:223], v198 offset:34816
	ds_read_b128 v[224:227], v198 offset:35840
	ds_read_b128 v[228:231], v198 offset:36864
	ds_read_b128 v[232:235], v198 offset:37888
	ds_read_b128 v[236:239], v198 offset:38912
	ds_read_b128 v[240:243], v198 offset:39936
	global_load_lds_dwordx4 v[208:209], off
	v_lshl_add_u64 v[208:209], s[20:21], 0, v[150:151]
	s_mov_b32 m0, s34
	s_nop 0
	global_load_lds_dwordx4 v[208:209], off
	s_waitcnt vmcnt(8)
	s_waitcnt lgkmcnt(0)
	s_barrier
	s_setprio 1
	s_waitcnt lgkmcnt(0)
	v_mfma_f32_16x16x32_bf16 v[140:143], v[120:123], v[200:203], v[140:143]
	v_mfma_f32_16x16x32_bf16 v[132:135], v[128:131], v[200:203], v[132:135]
	v_mfma_f32_16x16x32_bf16 v[108:111], v[120:123], v[220:223], v[108:111]
	v_mfma_f32_16x16x32_bf16 v[104:107], v[128:131], v[220:223], v[104:107]
	v_mfma_f32_16x16x32_bf16 v[92:95], v[120:123], v[228:231], v[92:95]
	v_mfma_f32_16x16x32_bf16 v[88:91], v[128:131], v[228:231], v[88:91]
	v_mfma_f32_16x16x32_bf16 v[76:79], v[120:123], v[236:239], v[76:79]
	v_mfma_f32_16x16x32_bf16 v[72:75], v[128:131], v[236:239], v[72:75]
	v_mfma_f32_16x16x32_bf16 v[140:143], v[124:127], v[204:207], v[140:143]
	v_mfma_f32_16x16x32_bf16 v[132:135], v[136:139], v[204:207], v[132:135]
	v_mfma_f32_16x16x32_bf16 v[108:111], v[124:127], v[224:227], v[108:111]
	v_mfma_f32_16x16x32_bf16 v[104:107], v[136:139], v[224:227], v[104:107]
	v_mfma_f32_16x16x32_bf16 v[92:95], v[124:127], v[232:235], v[92:95]
	v_mfma_f32_16x16x32_bf16 v[88:91], v[136:139], v[232:235], v[88:91]
	v_mfma_f32_16x16x32_bf16 v[76:79], v[124:127], v[240:243], v[76:79]
	v_mfma_f32_16x16x32_bf16 v[72:75], v[136:139], v[240:243], v[72:75]
	s_setprio 0
	s_setprio 1
	v_mfma_f32_16x16x32_bf16 v[116:119], v[144:147], v[200:203], v[116:119]
	v_mfma_f32_16x16x32_bf16 v[112:115], v[162:165], v[200:203], v[112:115]
	v_mfma_f32_16x16x32_bf16 v[100:103], v[144:147], v[220:223], v[100:103]
	v_mfma_f32_16x16x32_bf16 v[96:99], v[162:165], v[220:223], v[96:99]
	v_mfma_f32_16x16x32_bf16 v[84:87], v[144:147], v[228:231], v[84:87]
	v_mfma_f32_16x16x32_bf16 v[80:83], v[162:165], v[228:231], v[80:83]
	v_mfma_f32_16x16x32_bf16 v[68:71], v[144:147], v[236:239], v[68:71]
	v_mfma_f32_16x16x32_bf16 v[64:67], v[162:165], v[236:239], v[64:67]
	v_mfma_f32_16x16x32_bf16 v[116:119], v[158:161], v[204:207], v[116:119]
	v_mfma_f32_16x16x32_bf16 v[112:115], v[190:193], v[204:207], v[112:115]
	v_mfma_f32_16x16x32_bf16 v[100:103], v[158:161], v[224:227], v[100:103]
	v_mfma_f32_16x16x32_bf16 v[96:99], v[190:193], v[224:227], v[96:99]
	v_mfma_f32_16x16x32_bf16 v[84:87], v[158:161], v[232:235], v[84:87]
	v_mfma_f32_16x16x32_bf16 v[80:83], v[190:193], v[232:235], v[80:83]
	v_mfma_f32_16x16x32_bf16 v[68:71], v[158:161], v[240:243], v[68:71]
	v_mfma_f32_16x16x32_bf16 v[64:67], v[190:193], v[240:243], v[64:67]
	s_setprio 0
	s_barrier
	s_add_i32 s20, s60, s24
	v_lshl_add_u64 v[166:167], v[166:167], 0, s[50:51]
	s_mov_b32 m0, s20
	ds_read_b128 v[200:203], v198 offset:49152
	ds_read_b128 v[204:207], v198 offset:50176
	ds_read_b128 v[220:223], v198 offset:51200
	ds_read_b128 v[224:227], v198 offset:52224
	ds_read_b128 v[228:231], v198 offset:53248
	ds_read_b128 v[232:235], v198 offset:54272
	ds_read_b128 v[236:239], v198 offset:55296
	ds_read_b128 v[240:243], v198 offset:56320
	global_load_lds_dwordx4 v[166:167], off
	s_add_i32 m0, s20, 0x2000
	s_add_u32 s18, s18, 0x40080
	v_lshl_add_u64 v[166:167], v[178:179], 0, s[50:51]
	s_addc_u32 s19, s19, 0
	s_add_i32 s20, s61, s24
	global_load_lds_dwordx4 v[166:167], off
	v_lshl_add_u64 v[166:167], s[18:19], 0, v[168:169]
	s_mov_b32 m0, s20
	s_nop 0
	global_load_lds_dwordx4 v[166:167], off
	v_lshl_add_u64 v[166:167], s[18:19], 0, v[148:149]
	s_add_i32 m0, s20, 0x2000
	s_nop 0
	global_load_lds_dwordx4 v[166:167], off
	v_lshl_add_u64 v[166:167], v[180:181], 0, s[50:51]
	s_mov_b32 m0, s86
	s_nop 0
	global_load_lds_dwordx4 v[166:167], off
	v_lshl_add_u64 v[166:167], v[194:195], 0, s[50:51]
	s_mov_b32 m0, s87
	s_nop 0
	global_load_lds_dwordx4 v[166:167], off
	s_waitcnt vmcnt(8)
	s_waitcnt lgkmcnt(0)
	s_barrier
	s_setprio 1
	s_waitcnt lgkmcnt(0)
	v_mfma_f32_16x16x32_bf16 v[60:63], v[120:123], v[200:203], v[60:63]
	v_mfma_f32_16x16x32_bf16 v[56:59], v[128:131], v[200:203], v[56:59]
	v_mfma_f32_16x16x32_bf16 v[44:47], v[120:123], v[220:223], v[44:47]
	v_mfma_f32_16x16x32_bf16 v[40:43], v[128:131], v[220:223], v[40:43]
	v_mfma_f32_16x16x32_bf16 v[28:31], v[120:123], v[228:231], v[28:31]
	v_mfma_f32_16x16x32_bf16 v[24:27], v[128:131], v[228:231], v[24:27]
	v_mfma_f32_16x16x32_bf16 v[12:15], v[120:123], v[236:239], v[12:15]
	v_mfma_f32_16x16x32_bf16 v[8:11], v[128:131], v[236:239], v[8:11]
	v_mfma_f32_16x16x32_bf16 v[60:63], v[124:127], v[204:207], v[60:63]
	v_mfma_f32_16x16x32_bf16 v[56:59], v[136:139], v[204:207], v[56:59]
	v_mfma_f32_16x16x32_bf16 v[44:47], v[124:127], v[224:227], v[44:47]
	v_mfma_f32_16x16x32_bf16 v[40:43], v[136:139], v[224:227], v[40:43]
	v_mfma_f32_16x16x32_bf16 v[28:31], v[124:127], v[232:235], v[28:31]
	v_mfma_f32_16x16x32_bf16 v[24:27], v[136:139], v[232:235], v[24:27]
	v_mfma_f32_16x16x32_bf16 v[12:15], v[124:127], v[240:243], v[12:15]
	v_mfma_f32_16x16x32_bf16 v[8:11], v[136:139], v[240:243], v[8:11]
	s_setprio 0
	s_setprio 1
	v_mfma_f32_16x16x32_bf16 v[52:55], v[144:147], v[200:203], v[52:55]
	v_mfma_f32_16x16x32_bf16 v[48:51], v[162:165], v[200:203], v[48:51]
	v_mfma_f32_16x16x32_bf16 v[36:39], v[144:147], v[220:223], v[36:39]
	v_mfma_f32_16x16x32_bf16 v[32:35], v[162:165], v[220:223], v[32:35]
	v_mfma_f32_16x16x32_bf16 v[20:23], v[144:147], v[228:231], v[20:23]
	v_mfma_f32_16x16x32_bf16 v[16:19], v[162:165], v[228:231], v[16:19]
	v_mfma_f32_16x16x32_bf16 v[4:7], v[144:147], v[236:239], v[4:7]
	v_mfma_f32_16x16x32_bf16 v[0:3], v[162:165], v[236:239], v[0:3]
	v_mfma_f32_16x16x32_bf16 v[52:55], v[158:161], v[204:207], v[52:55]
	v_mfma_f32_16x16x32_bf16 v[48:51], v[190:193], v[204:207], v[48:51]
	v_mfma_f32_16x16x32_bf16 v[36:39], v[158:161], v[224:227], v[36:39]
	v_mfma_f32_16x16x32_bf16 v[32:35], v[190:193], v[224:227], v[32:35]
	v_mfma_f32_16x16x32_bf16 v[20:23], v[158:161], v[232:235], v[20:23]
	v_mfma_f32_16x16x32_bf16 v[16:19], v[190:193], v[232:235], v[16:19]
	v_mfma_f32_16x16x32_bf16 v[4:7], v[158:161], v[240:243], v[4:7]
	v_mfma_f32_16x16x32_bf16 v[0:3], v[190:193], v[240:243], v[0:3]
	s_add_i32 s90, s90, 2
	s_add_u32 s16, s16, 0x100
	s_addc_u32 s17, s17, 0
	s_add_u32 s58, s58, 0x100
	s_addc_u32 s59, s59, 0
	s_cmp_gt_u32 s90, 13
	s_setprio 0
	s_barrier
	s_cbranch_scc0 .LBB0_411
	s_and_b64 vcc, exec, s[6:7]
	s_cbranch_vccz .LBB0_414
	s_barrier

.LBB0_501:
	s_add_u32 s4, s0, 0xfffc0080
	s_addc_u32 s5, s1, -1
	s_add_i32 s60, 0, 0x10000
	s_cmp_eq_u32 vcc_lo, 12
	s_cselect_b32 s7, s15, s5
	s_cselect_b32 s6, s58, s4
	s_cselect_b32 s5, s13, s90
	s_cselect_b32 s4, s59, s87
	s_add_i32 vcc_hi, 0, 0x14000
	v_add_u32_e32 v158, s60, v164
	v_add_u32_e32 v162, vcc_hi, v164
	ds_read_b128 v[146:149], v158
	ds_read_b128 v[150:153], v158 offset:1024
	ds_read_b128 v[154:157], v158 offset:2048
	ds_read_b128 v[158:161], v158 offset:3072
	ds_read_b128 v[190:193], v162
	ds_read_b128 v[194:197], v162 offset:1024
	ds_read_b128 v[198:201], v162 offset:2048
	ds_read_b128 v[202:205], v162 offset:3072
	v_lshl_add_u64 v[162:163], s[0:1], 0, v[142:143]
	s_add_i32 m0, s23, 0xc000
	ds_read_b128 v[206:209], v166
	ds_read_b128 v[220:223], v166 offset:1024
	ds_read_b128 v[224:227], v166 offset:2048
	ds_read_b128 v[228:231], v166 offset:3072
	ds_read_b128 v[232:235], v166 offset:4096
	ds_read_b128 v[236:239], v166 offset:5120
	ds_read_b128 v[240:243], v166 offset:6144
	ds_read_b128 v[244:247], v166 offset:7168
	global_load_lds_dwordx4 v[162:163], off
	v_lshl_add_u64 v[162:163], s[0:1], 0, v[144:145]
	s_add_i32 m0, s23, 0xe000
	s_nop 0
	global_load_lds_dwordx4 v[162:163], off
	s_waitcnt vmcnt(8)
	s_waitcnt lgkmcnt(0)
	s_barrier
	s_setprio 1
	s_waitcnt lgkmcnt(0)
	v_mfma_f32_16x16x32_bf16 v[124:127], v[146:149], v[206:209], v[124:127]
	v_mfma_f32_16x16x32_bf16 v[120:123], v[154:157], v[206:209], v[120:123]
	v_mfma_f32_16x16x32_bf16 v[108:111], v[146:149], v[224:227], v[108:111]
	v_mfma_f32_16x16x32_bf16 v[104:107], v[154:157], v[224:227], v[104:107]
	v_mfma_f32_16x16x32_bf16 v[92:95], v[146:149], v[232:235], v[92:95]
	v_mfma_f32_16x16x32_bf16 v[88:91], v[154:157], v[232:235], v[88:91]
	v_mfma_f32_16x16x32_bf16 v[76:79], v[146:149], v[240:243], v[76:79]
	v_mfma_f32_16x16x32_bf16 v[72:75], v[154:157], v[240:243], v[72:75]
	v_mfma_f32_16x16x32_bf16 v[124:127], v[150:153], v[220:223], v[124:127]
	v_mfma_f32_16x16x32_bf16 v[120:123], v[158:161], v[220:223], v[120:123]
	v_mfma_f32_16x16x32_bf16 v[108:111], v[150:153], v[228:231], v[108:111]
	v_mfma_f32_16x16x32_bf16 v[104:107], v[158:161], v[228:231], v[104:107]
	v_mfma_f32_16x16x32_bf16 v[92:95], v[150:153], v[236:239], v[92:95]
	v_mfma_f32_16x16x32_bf16 v[88:91], v[158:161], v[236:239], v[88:91]
	v_mfma_f32_16x16x32_bf16 v[76:79], v[150:153], v[244:247], v[76:79]
	v_mfma_f32_16x16x32_bf16 v[72:75], v[158:161], v[244:247], v[72:75]
	s_setprio 0
	s_setprio 1
	v_mfma_f32_16x16x32_bf16 v[116:119], v[190:193], v[206:209], v[116:119]
	v_mfma_f32_16x16x32_bf16 v[112:115], v[198:201], v[206:209], v[112:115]
	v_mfma_f32_16x16x32_bf16 v[100:103], v[190:193], v[224:227], v[100:103]
	v_mfma_f32_16x16x32_bf16 v[96:99], v[198:201], v[224:227], v[96:99]
	v_mfma_f32_16x16x32_bf16 v[84:87], v[190:193], v[232:235], v[84:87]
	v_mfma_f32_16x16x32_bf16 v[80:83], v[198:201], v[232:235], v[80:83]
	v_mfma_f32_16x16x32_bf16 v[68:71], v[190:193], v[240:243], v[68:71]
	v_mfma_f32_16x16x32_bf16 v[64:67], v[198:201], v[240:243], v[64:67]
	v_mfma_f32_16x16x32_bf16 v[116:119], v[194:197], v[220:223], v[116:119]
	v_mfma_f32_16x16x32_bf16 v[112:115], v[202:205], v[220:223], v[112:115]
	v_mfma_f32_16x16x32_bf16 v[100:103], v[194:197], v[228:231], v[100:103]
	v_mfma_f32_16x16x32_bf16 v[96:99], v[202:205], v[228:231], v[96:99]
	v_mfma_f32_16x16x32_bf16 v[84:87], v[194:197], v[236:239], v[84:87]
	v_mfma_f32_16x16x32_bf16 v[80:83], v[202:205], v[236:239], v[80:83]
	v_mfma_f32_16x16x32_bf16 v[68:71], v[194:197], v[244:247], v[68:71]
	v_mfma_f32_16x16x32_bf16 v[64:67], v[202:205], v[244:247], v[64:67]
	s_setprio 0
	s_barrier
	s_add_i32 s60, s60, s22
	v_lshl_add_u64 v[162:163], s[4:5], 0, v[132:133]
	s_mov_b32 m0, s60
	ds_read_b128 v[206:209], v166 offset:16384
	ds_read_b128 v[220:223], v166 offset:17408
	ds_read_b128 v[224:227], v166 offset:18432
	ds_read_b128 v[228:231], v166 offset:19456
	ds_read_b128 v[232:235], v166 offset:20480
	ds_read_b128 v[236:239], v166 offset:21504
	ds_read_b128 v[240:243], v166 offset:22528
	ds_read_b128 v[244:247], v166 offset:23552
	global_load_lds_dwordx4 v[162:163], off
	s_add_i32 m0, s60, 0x2000
	s_add_u32 s60, s4, 0x40000
	v_lshl_add_u64 v[178:179], s[4:5], 0, v[128:129]
	s_addc_u32 s61, s5, 0
	s_add_i32 vcc_hi, vcc_hi, s22
	global_load_lds_dwordx4 v[178:179], off
	v_lshl_add_u64 v[180:181], s[60:61], 0, v[132:133]
	s_mov_b32 m0, vcc_hi
	v_lshl_add_u64 v[248:249], s[6:7], 0, v[130:131]
	global_load_lds_dwordx4 v[180:181], off
	v_lshl_add_u64 v[180:181], s[60:61], 0, v[128:129]
	s_add_i32 m0, vcc_hi, 0x2000
	s_nop 0
	global_load_lds_dwordx4 v[180:181], off
	v_lshl_add_u64 v[180:181], s[6:7], 0, v[134:135]
	s_mov_b32 m0, s23
	s_nop 0
	global_load_lds_dwordx4 v[180:181], off
	s_mov_b32 m0, s24
	s_nop 0
	global_load_lds_dwordx4 v[248:249], off
	s_waitcnt vmcnt(8)
	s_waitcnt lgkmcnt(0)
	s_barrier
	s_setprio 1
	s_waitcnt lgkmcnt(0)
	v_mfma_f32_16x16x32_bf16 v[60:63], v[146:149], v[206:209], v[60:63]
	v_mfma_f32_16x16x32_bf16 v[56:59], v[154:157], v[206:209], v[56:59]
	v_mfma_f32_16x16x32_bf16 v[44:47], v[146:149], v[224:227], v[44:47]
	v_mfma_f32_16x16x32_bf16 v[40:43], v[154:157], v[224:227], v[40:43]
	v_mfma_f32_16x16x32_bf16 v[28:31], v[146:149], v[232:235], v[28:31]
	v_mfma_f32_16x16x32_bf16 v[24:27], v[154:157], v[232:235], v[24:27]
	v_mfma_f32_16x16x32_bf16 v[12:15], v[146:149], v[240:243], v[12:15]
	v_mfma_f32_16x16x32_bf16 v[8:11], v[154:157], v[240:243], v[8:11]
	v_mfma_f32_16x16x32_bf16 v[60:63], v[150:153], v[220:223], v[60:63]
	v_mfma_f32_16x16x32_bf16 v[56:59], v[158:161], v[220:223], v[56:59]
	v_mfma_f32_16x16x32_bf16 v[44:47], v[150:153], v[228:231], v[44:47]
	v_mfma_f32_16x16x32_bf16 v[40:43], v[158:161], v[228:231], v[40:43]
	v_mfma_f32_16x16x32_bf16 v[28:31], v[150:153], v[236:239], v[28:31]
	v_mfma_f32_16x16x32_bf16 v[24:27], v[158:161], v[236:239], v[24:27]
	v_mfma_f32_16x16x32_bf16 v[12:15], v[150:153], v[244:247], v[12:15]
	v_mfma_f32_16x16x32_bf16 v[8:11], v[158:161], v[244:247], v[8:11]
	s_setprio 0
	s_setprio 1
	v_mfma_f32_16x16x32_bf16 v[52:55], v[190:193], v[206:209], v[52:55]
	v_mfma_f32_16x16x32_bf16 v[48:51], v[198:201], v[206:209], v[48:51]
	v_mfma_f32_16x16x32_bf16 v[36:39], v[190:193], v[224:227], v[36:39]
	v_mfma_f32_16x16x32_bf16 v[32:35], v[198:201], v[224:227], v[32:35]
	v_mfma_f32_16x16x32_bf16 v[20:23], v[190:193], v[232:235], v[20:23]
	v_mfma_f32_16x16x32_bf16 v[16:19], v[198:201], v[232:235], v[16:19]
	v_mfma_f32_16x16x32_bf16 v[4:7], v[190:193], v[240:243], v[4:7]
	v_mfma_f32_16x16x32_bf16 v[0:3], v[198:201], v[240:243], v[0:3]
	v_mfma_f32_16x16x32_bf16 v[52:55], v[194:197], v[220:223], v[52:55]
	v_mfma_f32_16x16x32_bf16 v[48:51], v[202:205], v[220:223], v[48:51]
	v_mfma_f32_16x16x32_bf16 v[36:39], v[194:197], v[228:231], v[36:39]
	v_mfma_f32_16x16x32_bf16 v[32:35], v[202:205], v[228:231], v[32:35]
	v_mfma_f32_16x16x32_bf16 v[20:23], v[194:197], v[236:239], v[20:23]
	v_mfma_f32_16x16x32_bf16 v[16:19], v[202:205], v[236:239], v[16:19]
	v_mfma_f32_16x16x32_bf16 v[4:7], v[194:197], v[244:247], v[4:7]
	v_mfma_f32_16x16x32_bf16 v[0:3], v[202:205], v[244:247], v[0:3]
	s_setprio 0
	s_barrier
	s_add_i32 s60, 0, 0x18000
	s_add_i32 s61, 0, 0x1c000
	v_add_u32_e32 v158, s60, v164
	v_add_u32_e32 v167, s61, v164
	ds_read_b128 v[146:149], v158
	ds_read_b128 v[150:153], v158 offset:1024
	ds_read_b128 v[154:157], v158 offset:2048
	ds_read_b128 v[158:161], v158 offset:3072
	ds_read_b128 v[190:193], v167
	ds_read_b128 v[194:197], v167 offset:1024
	ds_read_b128 v[198:201], v167 offset:2048
	ds_read_b128 v[202:205], v167 offset:3072
	s_add_u32 s6, s6, 0x40000
	s_addc_u32 s7, s7, 0
	s_mov_b32 m0, s25
	v_lshl_add_u64 v[250:251], s[6:7], 0, v[134:135]
	ds_read_b128 v[206:209], v166 offset:32768
	ds_read_b128 v[220:223], v166 offset:33792
	ds_read_b128 v[224:227], v166 offset:34816
	ds_read_b128 v[228:231], v166 offset:35840
	ds_read_b128 v[232:235], v166 offset:36864
	ds_read_b128 v[236:239], v166 offset:37888
	ds_read_b128 v[240:243], v166 offset:38912
	ds_read_b128 v[244:247], v166 offset:39936
	global_load_lds_dwordx4 v[250:251], off
	v_lshl_add_u64 v[250:251], s[6:7], 0, v[130:131]
	s_mov_b32 m0, s26
	s_nop 0
	global_load_lds_dwordx4 v[250:251], off
	s_waitcnt vmcnt(8)
	s_waitcnt lgkmcnt(0)
	s_barrier
	s_setprio 1
	s_waitcnt lgkmcnt(0)
	v_mfma_f32_16x16x32_bf16 v[124:127], v[146:149], v[206:209], v[124:127]
	v_mfma_f32_16x16x32_bf16 v[120:123], v[154:157], v[206:209], v[120:123]
	v_mfma_f32_16x16x32_bf16 v[108:111], v[146:149], v[224:227], v[108:111]
	v_mfma_f32_16x16x32_bf16 v[104:107], v[154:157], v[224:227], v[104:107]
	v_mfma_f32_16x16x32_bf16 v[92:95], v[146:149], v[232:235], v[92:95]
	v_mfma_f32_16x16x32_bf16 v[88:91], v[154:157], v[232:235], v[88:91]
	v_mfma_f32_16x16x32_bf16 v[76:79], v[146:149], v[240:243], v[76:79]
	v_mfma_f32_16x16x32_bf16 v[72:75], v[154:157], v[240:243], v[72:75]
	v_mfma_f32_16x16x32_bf16 v[124:127], v[150:153], v[220:223], v[124:127]
	v_mfma_f32_16x16x32_bf16 v[120:123], v[158:161], v[220:223], v[120:123]
	v_mfma_f32_16x16x32_bf16 v[108:111], v[150:153], v[228:231], v[108:111]
	v_mfma_f32_16x16x32_bf16 v[104:107], v[158:161], v[228:231], v[104:107]
	v_mfma_f32_16x16x32_bf16 v[92:95], v[150:153], v[236:239], v[92:95]
	v_mfma_f32_16x16x32_bf16 v[88:91], v[158:161], v[236:239], v[88:91]
	v_mfma_f32_16x16x32_bf16 v[76:79], v[150:153], v[244:247], v[76:79]
	v_mfma_f32_16x16x32_bf16 v[72:75], v[158:161], v[244:247], v[72:75]
	s_setprio 0
	s_setprio 1
	v_mfma_f32_16x16x32_bf16 v[116:119], v[190:193], v[206:209], v[116:119]
	v_mfma_f32_16x16x32_bf16 v[112:115], v[198:201], v[206:209], v[112:115]
	v_mfma_f32_16x16x32_bf16 v[100:103], v[190:193], v[224:227], v[100:103]
	v_mfma_f32_16x16x32_bf16 v[96:99], v[198:201], v[224:227], v[96:99]
	v_mfma_f32_16x16x32_bf16 v[84:87], v[190:193], v[232:235], v[84:87]
	v_mfma_f32_16x16x32_bf16 v[80:83], v[198:201], v[232:235], v[80:83]
	v_mfma_f32_16x16x32_bf16 v[68:71], v[190:193], v[240:243], v[68:71]
	v_mfma_f32_16x16x32_bf16 v[64:67], v[198:201], v[240:243], v[64:67]
	v_mfma_f32_16x16x32_bf16 v[116:119], v[194:197], v[220:223], v[116:119]
	v_mfma_f32_16x16x32_bf16 v[112:115], v[202:205], v[220:223], v[112:115]
	v_mfma_f32_16x16x32_bf16 v[100:103], v[194:197], v[228:231], v[100:103]
	v_mfma_f32_16x16x32_bf16 v[96:99], v[202:205], v[228:231], v[96:99]
	v_mfma_f32_16x16x32_bf16 v[84:87], v[194:197], v[236:239], v[84:87]
	v_mfma_f32_16x16x32_bf16 v[80:83], v[202:205], v[236:239], v[80:83]
	v_mfma_f32_16x16x32_bf16 v[68:71], v[194:197], v[244:247], v[68:71]
	v_mfma_f32_16x16x32_bf16 v[64:67], v[202:205], v[244:247], v[64:67]
	s_setprio 0
	s_barrier
	s_add_i32 s6, s60, s22
	v_lshl_add_u64 v[162:163], v[162:163], 0, s[50:51]
	s_mov_b32 m0, s6
	ds_read_b128 v[206:209], v166 offset:49152
	ds_read_b128 v[220:223], v166 offset:50176
	ds_read_b128 v[224:227], v166 offset:51200
	ds_read_b128 v[228:231], v166 offset:52224
	ds_read_b128 v[232:235], v166 offset:53248
	ds_read_b128 v[236:239], v166 offset:54272
	ds_read_b128 v[240:243], v166 offset:55296
	ds_read_b128 v[244:247], v166 offset:56320
	global_load_lds_dwordx4 v[162:163], off
	s_add_i32 m0, s6, 0x2000
	s_add_u32 s4, s4, 0x40080
	v_lshl_add_u64 v[162:163], v[178:179], 0, s[50:51]
	s_addc_u32 s5, s5, 0
	s_add_i32 s6, s61, s22
	global_load_lds_dwordx4 v[162:163], off
	v_lshl_add_u64 v[162:163], s[4:5], 0, v[132:133]
	s_mov_b32 m0, s6
	s_nop 0
	global_load_lds_dwordx4 v[162:163], off
	v_lshl_add_u64 v[162:163], s[4:5], 0, v[128:129]
	s_add_i32 m0, s6, 0x2000
	s_nop 0
	global_load_lds_dwordx4 v[162:163], off
	v_lshl_add_u64 v[162:163], v[180:181], 0, s[50:51]
	s_mov_b32 m0, s34
	s_nop 0
	global_load_lds_dwordx4 v[162:163], off
	v_lshl_add_u64 v[162:163], v[248:249], 0, s[50:51]
	s_mov_b32 m0, s35
	s_nop 0
	global_load_lds_dwordx4 v[162:163], off
	s_waitcnt vmcnt(8)
	s_waitcnt lgkmcnt(0)
	s_barrier
	s_setprio 1
	s_waitcnt lgkmcnt(0)
	v_mfma_f32_16x16x32_bf16 v[60:63], v[146:149], v[206:209], v[60:63]
	v_mfma_f32_16x16x32_bf16 v[56:59], v[154:157], v[206:209], v[56:59]
	v_mfma_f32_16x16x32_bf16 v[44:47], v[146:149], v[224:227], v[44:47]
	v_mfma_f32_16x16x32_bf16 v[40:43], v[154:157], v[224:227], v[40:43]
	v_mfma_f32_16x16x32_bf16 v[28:31], v[146:149], v[232:235], v[28:31]
	v_mfma_f32_16x16x32_bf16 v[24:27], v[154:157], v[232:235], v[24:27]
	v_mfma_f32_16x16x32_bf16 v[12:15], v[146:149], v[240:243], v[12:15]
	v_mfma_f32_16x16x32_bf16 v[8:11], v[154:157], v[240:243], v[8:11]
	v_mfma_f32_16x16x32_bf16 v[60:63], v[150:153], v[220:223], v[60:63]
	v_mfma_f32_16x16x32_bf16 v[56:59], v[158:161], v[220:223], v[56:59]
	v_mfma_f32_16x16x32_bf16 v[44:47], v[150:153], v[228:231], v[44:47]
	v_mfma_f32_16x16x32_bf16 v[40:43], v[158:161], v[228:231], v[40:43]
	v_mfma_f32_16x16x32_bf16 v[28:31], v[150:153], v[236:239], v[28:31]
	v_mfma_f32_16x16x32_bf16 v[24:27], v[158:161], v[236:239], v[24:27]
	v_mfma_f32_16x16x32_bf16 v[12:15], v[150:153], v[244:247], v[12:15]
	v_mfma_f32_16x16x32_bf16 v[8:11], v[158:161], v[244:247], v[8:11]
	s_setprio 0
	s_setprio 1
	v_mfma_f32_16x16x32_bf16 v[52:55], v[190:193], v[206:209], v[52:55]
	v_mfma_f32_16x16x32_bf16 v[48:51], v[198:201], v[206:209], v[48:51]
	v_mfma_f32_16x16x32_bf16 v[36:39], v[190:193], v[224:227], v[36:39]
	v_mfma_f32_16x16x32_bf16 v[32:35], v[198:201], v[224:227], v[32:35]
	v_mfma_f32_16x16x32_bf16 v[20:23], v[190:193], v[232:235], v[20:23]
	v_mfma_f32_16x16x32_bf16 v[16:19], v[198:201], v[232:235], v[16:19]
	v_mfma_f32_16x16x32_bf16 v[4:7], v[190:193], v[240:243], v[4:7]
	v_mfma_f32_16x16x32_bf16 v[0:3], v[198:201], v[240:243], v[0:3]
	v_mfma_f32_16x16x32_bf16 v[52:55], v[194:197], v[220:223], v[52:55]
	v_mfma_f32_16x16x32_bf16 v[48:51], v[202:205], v[220:223], v[48:51]
	v_mfma_f32_16x16x32_bf16 v[36:39], v[194:197], v[228:231], v[36:39]
	v_mfma_f32_16x16x32_bf16 v[32:35], v[202:205], v[228:231], v[32:35]
	v_mfma_f32_16x16x32_bf16 v[20:23], v[194:197], v[236:239], v[20:23]
	v_mfma_f32_16x16x32_bf16 v[16:19], v[202:205], v[236:239], v[16:19]
	v_mfma_f32_16x16x32_bf16 v[4:7], v[194:197], v[244:247], v[4:7]
	v_mfma_f32_16x16x32_bf16 v[0:3], v[202:205], v[244:247], v[0:3]
	s_add_i32 vcc_lo, vcc_lo, 2
	s_add_u32 s0, s0, 0x100
	s_addc_u32 s1, s1, 0
	s_add_u32 s87, s87, 0x100
	s_addc_u32 s90, s90, 0
	s_cmp_gt_u32 vcc_lo, 13
	s_setprio 0
	s_barrier
	s_cbranch_scc0 .LBB0_501
	s_and_b64 vcc, exec, s[10:11]
	s_cbranch_vccz .LBB0_504
	s_barrier

.LBB0_635:
	s_add_u32 s14, s12, 0x100
	s_addc_u32 s15, s13, 0
	s_add_i32 s60, 0, 0x10000
	v_add_u32_e32 v94, s60, v77
	ds_read_b128 v[82:85], v94
	ds_read_b128 v[86:89], v94 offset:1024
	ds_read_b128 v[90:93], v94 offset:2048
	ds_read_b128 v[94:97], v94 offset:3072
	s_cmp_eq_u32 s90, 4
	s_cselect_b32 s19, s9, s15
	s_cselect_b32 s18, s8, s14
	s_cselect_b32 s17, s7, s87
	s_cselect_b32 s16, s59, s86
	v_lshl_add_u64 v[130:131], s[12:13], 0, v[72:73]
	s_add_i32 m0, s23, 0xc000
	ds_read_b128 v[98:101], v81
	ds_read_b128 v[102:105], v81 offset:1024
	ds_read_b128 v[106:109], v81 offset:2048
	ds_read_b128 v[110:113], v81 offset:3072
	ds_read_b128 v[114:117], v81 offset:4096
	ds_read_b128 v[118:121], v81 offset:5120
	ds_read_b128 v[122:125], v81 offset:6144
	ds_read_b128 v[126:129], v81 offset:7168
	global_load_lds_dwordx4 v[130:131], off
	v_lshl_add_u64 v[130:131], s[12:13], 0, v[74:75]
	s_add_i32 m0, s23, 0xe000
	s_nop 0
	global_load_lds_dwordx4 v[130:131], off
	s_waitcnt vmcnt(8)
	s_waitcnt lgkmcnt(0)
	s_barrier
	s_setprio 1
	s_waitcnt lgkmcnt(0)
	v_mfma_f32_16x16x32_bf16 v[60:63], v[82:85], v[98:101], v[60:63]
	v_mfma_f32_16x16x32_bf16 v[56:59], v[90:93], v[98:101], v[56:59]
	v_mfma_f32_16x16x32_bf16 v[52:55], v[82:85], v[106:109], v[52:55]
	v_mfma_f32_16x16x32_bf16 v[48:51], v[90:93], v[106:109], v[48:51]
	v_mfma_f32_16x16x32_bf16 v[44:47], v[82:85], v[114:117], v[44:47]
	v_mfma_f32_16x16x32_bf16 v[40:43], v[90:93], v[114:117], v[40:43]
	v_mfma_f32_16x16x32_bf16 v[36:39], v[82:85], v[122:125], v[36:39]
	v_mfma_f32_16x16x32_bf16 v[32:35], v[90:93], v[122:125], v[32:35]
	v_mfma_f32_16x16x32_bf16 v[60:63], v[86:89], v[102:105], v[60:63]
	v_mfma_f32_16x16x32_bf16 v[56:59], v[94:97], v[102:105], v[56:59]
	v_mfma_f32_16x16x32_bf16 v[52:55], v[86:89], v[110:113], v[52:55]
	v_mfma_f32_16x16x32_bf16 v[48:51], v[94:97], v[110:113], v[48:51]
	v_mfma_f32_16x16x32_bf16 v[44:47], v[86:89], v[118:121], v[44:47]
	v_mfma_f32_16x16x32_bf16 v[40:43], v[94:97], v[118:121], v[40:43]
	v_mfma_f32_16x16x32_bf16 v[36:39], v[86:89], v[126:129], v[36:39]
	v_mfma_f32_16x16x32_bf16 v[32:35], v[94:97], v[126:129], v[32:35]
	s_setprio 0
	s_setprio 1
	s_setprio 0
	s_barrier
	s_add_i32 s12, s60, s22
	v_lshl_add_u64 v[130:131], s[16:17], 0, v[168:169]
	s_mov_b32 m0, s12
	ds_read_b128 v[98:101], v81 offset:16384
	ds_read_b128 v[102:105], v81 offset:17408
	ds_read_b128 v[106:109], v81 offset:18432
	ds_read_b128 v[110:113], v81 offset:19456
	ds_read_b128 v[114:117], v81 offset:20480
	ds_read_b128 v[118:121], v81 offset:21504
	ds_read_b128 v[122:125], v81 offset:22528
	ds_read_b128 v[126:129], v81 offset:23552
	global_load_lds_dwordx4 v[130:131], off
	s_add_i32 m0, s12, 0x2000
	s_add_u32 s12, s16, 0x20000
	v_lshl_add_u64 v[132:133], s[16:17], 0, v[64:65]
	s_addc_u32 s13, s17, 0
	global_load_lds_dwordx4 v[132:133], off
	v_lshl_add_u64 v[134:135], s[12:13], 0, v[168:169]
	s_mov_b32 m0, s24
	v_lshl_add_u64 v[136:137], s[18:19], 0, v[66:67]
	global_load_lds_dwordx4 v[134:135], off
	v_lshl_add_u64 v[134:135], s[12:13], 0, v[64:65]
	s_mov_b32 m0, s25
	s_nop 0
	global_load_lds_dwordx4 v[134:135], off
	v_lshl_add_u64 v[134:135], s[18:19], 0, v[68:69]
	s_mov_b32 m0, s23
	s_nop 0
	global_load_lds_dwordx4 v[134:135], off
	s_mov_b32 m0, s26
	s_nop 0
	global_load_lds_dwordx4 v[136:137], off
	s_waitcnt vmcnt(8)
	s_waitcnt lgkmcnt(0)
	s_barrier
	s_setprio 1
	s_waitcnt lgkmcnt(0)
	v_mfma_f32_16x16x32_bf16 v[28:31], v[82:85], v[98:101], v[28:31]
	v_mfma_f32_16x16x32_bf16 v[24:27], v[90:93], v[98:101], v[24:27]
	v_mfma_f32_16x16x32_bf16 v[20:23], v[82:85], v[106:109], v[20:23]
	v_mfma_f32_16x16x32_bf16 v[16:19], v[90:93], v[106:109], v[16:19]
	v_mfma_f32_16x16x32_bf16 v[12:15], v[82:85], v[114:117], v[12:15]
	v_mfma_f32_16x16x32_bf16 v[8:11], v[90:93], v[114:117], v[8:11]
	v_mfma_f32_16x16x32_bf16 v[4:7], v[82:85], v[122:125], v[4:7]
	v_mfma_f32_16x16x32_bf16 v[0:3], v[90:93], v[122:125], v[0:3]
	v_mfma_f32_16x16x32_bf16 v[28:31], v[86:89], v[102:105], v[28:31]
	v_mfma_f32_16x16x32_bf16 v[24:27], v[94:97], v[102:105], v[24:27]
	v_mfma_f32_16x16x32_bf16 v[20:23], v[86:89], v[110:113], v[20:23]
	v_mfma_f32_16x16x32_bf16 v[16:19], v[94:97], v[110:113], v[16:19]
	v_mfma_f32_16x16x32_bf16 v[12:15], v[86:89], v[118:121], v[12:15]
	v_mfma_f32_16x16x32_bf16 v[8:11], v[94:97], v[118:121], v[8:11]
	v_mfma_f32_16x16x32_bf16 v[4:7], v[86:89], v[126:129], v[4:7]
	v_mfma_f32_16x16x32_bf16 v[0:3], v[94:97], v[126:129], v[0:3]
	s_setprio 0
	s_setprio 1
	s_setprio 0
	s_barrier
	s_add_i32 s60, 0, 0x18000
	v_add_u32_e32 v94, s60, v77
	ds_read_b128 v[82:85], v94
	ds_read_b128 v[86:89], v94 offset:1024
	ds_read_b128 v[90:93], v94 offset:2048
	ds_read_b128 v[94:97], v94 offset:3072
	s_add_u32 s12, s18, 0x28000
	s_addc_u32 s13, s19, 0
	s_mov_b32 m0, s27
	v_lshl_add_u64 v[138:139], s[12:13], 0, v[68:69]
	ds_read_b128 v[98:101], v81 offset:32768
	ds_read_b128 v[102:105], v81 offset:33792
	ds_read_b128 v[106:109], v81 offset:34816
	ds_read_b128 v[110:113], v81 offset:35840
	ds_read_b128 v[114:117], v81 offset:36864
	ds_read_b128 v[118:121], v81 offset:37888
	ds_read_b128 v[122:125], v81 offset:38912
	ds_read_b128 v[126:129], v81 offset:39936
	global_load_lds_dwordx4 v[138:139], off
	v_lshl_add_u64 v[138:139], s[12:13], 0, v[66:67]
	s_mov_b32 m0, s34
	s_nop 0
	global_load_lds_dwordx4 v[138:139], off
	s_waitcnt vmcnt(8)
	s_waitcnt lgkmcnt(0)
	s_barrier
	s_setprio 1
	s_waitcnt lgkmcnt(0)
	v_mfma_f32_16x16x32_bf16 v[60:63], v[82:85], v[98:101], v[60:63]
	v_mfma_f32_16x16x32_bf16 v[56:59], v[90:93], v[98:101], v[56:59]
	v_mfma_f32_16x16x32_bf16 v[52:55], v[82:85], v[106:109], v[52:55]
	v_mfma_f32_16x16x32_bf16 v[48:51], v[90:93], v[106:109], v[48:51]
	v_mfma_f32_16x16x32_bf16 v[44:47], v[82:85], v[114:117], v[44:47]
	v_mfma_f32_16x16x32_bf16 v[40:43], v[90:93], v[114:117], v[40:43]
	v_mfma_f32_16x16x32_bf16 v[36:39], v[82:85], v[122:125], v[36:39]
	v_mfma_f32_16x16x32_bf16 v[32:35], v[90:93], v[122:125], v[32:35]
	v_mfma_f32_16x16x32_bf16 v[60:63], v[86:89], v[102:105], v[60:63]
	v_mfma_f32_16x16x32_bf16 v[56:59], v[94:97], v[102:105], v[56:59]
	v_mfma_f32_16x16x32_bf16 v[52:55], v[86:89], v[110:113], v[52:55]
	v_mfma_f32_16x16x32_bf16 v[48:51], v[94:97], v[110:113], v[48:51]
	v_mfma_f32_16x16x32_bf16 v[44:47], v[86:89], v[118:121], v[44:47]
	v_mfma_f32_16x16x32_bf16 v[40:43], v[94:97], v[118:121], v[40:43]
	v_mfma_f32_16x16x32_bf16 v[36:39], v[86:89], v[126:129], v[36:39]
	v_mfma_f32_16x16x32_bf16 v[32:35], v[94:97], v[126:129], v[32:35]
	s_setprio 0
	s_setprio 1
	s_setprio 0
	s_barrier
	s_add_i32 s12, s60, s22
	v_lshl_add_u64 v[130:131], v[130:131], 0, s[50:51]
	s_mov_b32 m0, s12
	ds_read_b128 v[98:101], v81 offset:49152
	ds_read_b128 v[102:105], v81 offset:50176
	ds_read_b128 v[106:109], v81 offset:51200
	ds_read_b128 v[110:113], v81 offset:52224
	ds_read_b128 v[114:117], v81 offset:53248
	ds_read_b128 v[118:121], v81 offset:54272
	ds_read_b128 v[122:125], v81 offset:55296
	ds_read_b128 v[126:129], v81 offset:56320
	global_load_lds_dwordx4 v[130:131], off
	s_add_i32 m0, s12, 0x2000
	s_add_u32 s12, s16, 0x20080
	v_lshl_add_u64 v[130:131], v[132:133], 0, s[50:51]
	s_addc_u32 s13, s17, 0
	global_load_lds_dwordx4 v[130:131], off
	v_lshl_add_u64 v[130:131], s[12:13], 0, v[168:169]
	s_mov_b32 m0, s54
	s_nop 0
	global_load_lds_dwordx4 v[130:131], off
	v_lshl_add_u64 v[130:131], s[12:13], 0, v[64:65]
	s_mov_b32 m0, s55
	s_nop 0
	global_load_lds_dwordx4 v[130:131], off
	v_lshl_add_u64 v[130:131], v[134:135], 0, s[50:51]
	s_mov_b32 m0, s35
	s_nop 0
	global_load_lds_dwordx4 v[130:131], off
	v_lshl_add_u64 v[130:131], v[136:137], 0, s[50:51]
	s_mov_b32 m0, s36
	s_nop 0
	global_load_lds_dwordx4 v[130:131], off
	s_waitcnt vmcnt(8)
	s_waitcnt lgkmcnt(0)
	s_barrier
	s_setprio 1
	s_waitcnt lgkmcnt(0)
	v_mfma_f32_16x16x32_bf16 v[28:31], v[82:85], v[98:101], v[28:31]
	v_mfma_f32_16x16x32_bf16 v[24:27], v[90:93], v[98:101], v[24:27]
	v_mfma_f32_16x16x32_bf16 v[20:23], v[82:85], v[106:109], v[20:23]
	v_mfma_f32_16x16x32_bf16 v[16:19], v[90:93], v[106:109], v[16:19]
	v_mfma_f32_16x16x32_bf16 v[12:15], v[82:85], v[114:117], v[12:15]
	v_mfma_f32_16x16x32_bf16 v[8:11], v[90:93], v[114:117], v[8:11]
	v_mfma_f32_16x16x32_bf16 v[4:7], v[82:85], v[122:125], v[4:7]
	v_mfma_f32_16x16x32_bf16 v[0:3], v[90:93], v[122:125], v[0:3]
	v_mfma_f32_16x16x32_bf16 v[28:31], v[86:89], v[102:105], v[28:31]
	v_mfma_f32_16x16x32_bf16 v[24:27], v[94:97], v[102:105], v[24:27]
	v_mfma_f32_16x16x32_bf16 v[20:23], v[86:89], v[110:113], v[20:23]
	v_mfma_f32_16x16x32_bf16 v[16:19], v[94:97], v[110:113], v[16:19]
	v_mfma_f32_16x16x32_bf16 v[12:15], v[86:89], v[118:121], v[12:15]
	v_mfma_f32_16x16x32_bf16 v[8:11], v[94:97], v[118:121], v[8:11]
	v_mfma_f32_16x16x32_bf16 v[4:7], v[86:89], v[126:129], v[4:7]
	v_mfma_f32_16x16x32_bf16 v[0:3], v[94:97], v[126:129], v[0:3]
	s_setprio 0
	s_setprio 1
	s_add_i32 s90, s90, 2
	s_add_u32 s86, s86, 0x100
	s_addc_u32 s87, s87, 0
	s_cmp_gt_u32 s90, 5
	s_mov_b64 s[12:13], s[14:15]
	s_setprio 0
	s_barrier
	s_cbranch_scc0 .LBB0_635
	s_and_b64 vcc, exec, s[4:5]
	s_mov_b32 s63, 0x200000
	s_mov_b32 s64, s95
	s_cbranch_vccz .LBB0_638
	s_barrier

.LBB0_797:
	s_add_u32 s14, s12, 0x100
	s_addc_u32 s15, s13, 0
	s_add_i32 s58, 0, 0x10000
	s_cmp_eq_u32 s57, 6
	s_cselect_b32 s19, s9, s15
	s_cselect_b32 s18, s8, s14
	s_cselect_b32 s17, s11, s56
	s_cselect_b32 s16, s10, s55
	s_add_i32 s59, 0, 0x14000
	v_add_u32_e32 v156, s58, v141
	v_add_u32_e32 v170, s59, v141
	ds_read_b128 v[144:147], v156
	ds_read_b128 v[148:151], v156 offset:1024
	ds_read_b128 v[152:155], v156 offset:2048
	ds_read_b128 v[156:159], v156 offset:3072
	ds_read_b128 v[160:163], v170
	ds_read_b128 v[164:167], v170 offset:1024
	ds_read_b128 v[190:193], v170 offset:2048
	ds_read_b128 v[194:197], v170 offset:3072
	v_lshl_add_u64 v[178:179], s[12:13], 0, v[136:137]
	s_add_i32 m0, s23, 0xc000
	ds_read_b128 v[198:201], v143
	ds_read_b128 v[202:205], v143 offset:1024
	ds_read_b128 v[206:209], v143 offset:2048
	ds_read_b128 v[220:223], v143 offset:3072
	ds_read_b128 v[224:227], v143 offset:4096
	ds_read_b128 v[228:231], v143 offset:5120
	ds_read_b128 v[232:235], v143 offset:6144
	ds_read_b128 v[236:239], v143 offset:7168
	global_load_lds_dwordx4 v[178:179], off
	v_lshl_add_u64 v[178:179], s[12:13], 0, v[138:139]
	s_add_i32 m0, s23, 0xe000
	s_nop 0
	global_load_lds_dwordx4 v[178:179], off
	s_waitcnt vmcnt(8)
	s_waitcnt lgkmcnt(0)
	s_barrier
	s_setprio 1
	s_waitcnt lgkmcnt(0)
	v_mfma_f32_16x16x32_bf16 v[124:127], v[144:147], v[198:201], v[124:127]
	v_mfma_f32_16x16x32_bf16 v[120:123], v[152:155], v[198:201], v[120:123]
	v_mfma_f32_16x16x32_bf16 v[108:111], v[144:147], v[206:209], v[108:111]
	v_mfma_f32_16x16x32_bf16 v[104:107], v[152:155], v[206:209], v[104:107]
	v_mfma_f32_16x16x32_bf16 v[92:95], v[144:147], v[224:227], v[92:95]
	v_mfma_f32_16x16x32_bf16 v[88:91], v[152:155], v[224:227], v[88:91]
	v_mfma_f32_16x16x32_bf16 v[76:79], v[144:147], v[232:235], v[76:79]
	v_mfma_f32_16x16x32_bf16 v[72:75], v[152:155], v[232:235], v[72:75]
	v_mfma_f32_16x16x32_bf16 v[124:127], v[148:151], v[202:205], v[124:127]
	v_mfma_f32_16x16x32_bf16 v[120:123], v[156:159], v[202:205], v[120:123]
	v_mfma_f32_16x16x32_bf16 v[108:111], v[148:151], v[220:223], v[108:111]
	v_mfma_f32_16x16x32_bf16 v[104:107], v[156:159], v[220:223], v[104:107]
	v_mfma_f32_16x16x32_bf16 v[92:95], v[148:151], v[228:231], v[92:95]
	v_mfma_f32_16x16x32_bf16 v[88:91], v[156:159], v[228:231], v[88:91]
	v_mfma_f32_16x16x32_bf16 v[76:79], v[148:151], v[236:239], v[76:79]
	v_mfma_f32_16x16x32_bf16 v[72:75], v[156:159], v[236:239], v[72:75]
	s_setprio 0
	s_setprio 1
	v_mfma_f32_16x16x32_bf16 v[116:119], v[160:163], v[198:201], v[116:119]
	v_mfma_f32_16x16x32_bf16 v[112:115], v[190:193], v[198:201], v[112:115]
	v_mfma_f32_16x16x32_bf16 v[100:103], v[160:163], v[206:209], v[100:103]
	v_mfma_f32_16x16x32_bf16 v[96:99], v[190:193], v[206:209], v[96:99]
	v_mfma_f32_16x16x32_bf16 v[84:87], v[160:163], v[224:227], v[84:87]
	v_mfma_f32_16x16x32_bf16 v[80:83], v[190:193], v[224:227], v[80:83]
	v_mfma_f32_16x16x32_bf16 v[68:71], v[160:163], v[232:235], v[68:71]
	v_mfma_f32_16x16x32_bf16 v[64:67], v[190:193], v[232:235], v[64:67]
	v_mfma_f32_16x16x32_bf16 v[116:119], v[164:167], v[202:205], v[116:119]
	v_mfma_f32_16x16x32_bf16 v[112:115], v[194:197], v[202:205], v[112:115]
	v_mfma_f32_16x16x32_bf16 v[100:103], v[164:167], v[220:223], v[100:103]
	v_mfma_f32_16x16x32_bf16 v[96:99], v[194:197], v[220:223], v[96:99]
	v_mfma_f32_16x16x32_bf16 v[84:87], v[164:167], v[228:231], v[84:87]
	v_mfma_f32_16x16x32_bf16 v[80:83], v[194:197], v[228:231], v[80:83]
	v_mfma_f32_16x16x32_bf16 v[68:71], v[164:167], v[236:239], v[68:71]
	v_mfma_f32_16x16x32_bf16 v[64:67], v[194:197], v[236:239], v[64:67]
	s_setprio 0
	s_barrier
	s_add_i32 s12, s58, s22
	v_lshl_add_u64 v[178:179], s[16:17], 0, v[132:133]
	s_mov_b32 m0, s12
	ds_read_b128 v[198:201], v143 offset:16384
	ds_read_b128 v[202:205], v143 offset:17408
	ds_read_b128 v[206:209], v143 offset:18432
	ds_read_b128 v[220:223], v143 offset:19456
	ds_read_b128 v[224:227], v143 offset:20480
	ds_read_b128 v[228:231], v143 offset:21504
	ds_read_b128 v[232:235], v143 offset:22528
	ds_read_b128 v[236:239], v143 offset:23552
	global_load_lds_dwordx4 v[178:179], off
	s_add_i32 m0, s12, 0x2000
	s_add_u32 s12, s16, 0x28000
	v_lshl_add_u64 v[180:181], s[16:17], 0, v[128:129]
	s_addc_u32 s13, s17, 0
	s_add_i32 s58, s59, s22
	global_load_lds_dwordx4 v[180:181], off
	v_lshl_add_u64 v[240:241], s[12:13], 0, v[132:133]
	s_mov_b32 m0, s58
	v_lshl_add_u64 v[242:243], s[18:19], 0, v[130:131]
	global_load_lds_dwordx4 v[240:241], off
	v_lshl_add_u64 v[240:241], s[12:13], 0, v[128:129]
	s_add_i32 m0, s58, 0x2000
	s_nop 0
	global_load_lds_dwordx4 v[240:241], off
	v_lshl_add_u64 v[240:241], s[18:19], 0, v[134:135]
	s_mov_b32 m0, s23
	s_nop 0
	global_load_lds_dwordx4 v[240:241], off
	s_mov_b32 m0, s24
	s_nop 0
	global_load_lds_dwordx4 v[242:243], off
	s_waitcnt vmcnt(8)
	s_waitcnt lgkmcnt(0)
	s_barrier
	s_setprio 1
	s_waitcnt lgkmcnt(0)
	v_mfma_f32_16x16x32_bf16 v[60:63], v[144:147], v[198:201], v[60:63]
	v_mfma_f32_16x16x32_bf16 v[56:59], v[152:155], v[198:201], v[56:59]
	v_mfma_f32_16x16x32_bf16 v[44:47], v[144:147], v[206:209], v[44:47]
	v_mfma_f32_16x16x32_bf16 v[40:43], v[152:155], v[206:209], v[40:43]
	v_mfma_f32_16x16x32_bf16 v[28:31], v[144:147], v[224:227], v[28:31]
	v_mfma_f32_16x16x32_bf16 v[24:27], v[152:155], v[224:227], v[24:27]
	v_mfma_f32_16x16x32_bf16 v[12:15], v[144:147], v[232:235], v[12:15]
	v_mfma_f32_16x16x32_bf16 v[8:11], v[152:155], v[232:235], v[8:11]
	v_mfma_f32_16x16x32_bf16 v[60:63], v[148:151], v[202:205], v[60:63]
	v_mfma_f32_16x16x32_bf16 v[56:59], v[156:159], v[202:205], v[56:59]
	v_mfma_f32_16x16x32_bf16 v[44:47], v[148:151], v[220:223], v[44:47]
	v_mfma_f32_16x16x32_bf16 v[40:43], v[156:159], v[220:223], v[40:43]
	v_mfma_f32_16x16x32_bf16 v[28:31], v[148:151], v[228:231], v[28:31]
	v_mfma_f32_16x16x32_bf16 v[24:27], v[156:159], v[228:231], v[24:27]
	v_mfma_f32_16x16x32_bf16 v[12:15], v[148:151], v[236:239], v[12:15]
	v_mfma_f32_16x16x32_bf16 v[8:11], v[156:159], v[236:239], v[8:11]
	s_setprio 0
	s_setprio 1
	v_mfma_f32_16x16x32_bf16 v[52:55], v[160:163], v[198:201], v[52:55]
	v_mfma_f32_16x16x32_bf16 v[48:51], v[190:193], v[198:201], v[48:51]
	v_mfma_f32_16x16x32_bf16 v[36:39], v[160:163], v[206:209], v[36:39]
	v_mfma_f32_16x16x32_bf16 v[32:35], v[190:193], v[206:209], v[32:35]
	v_mfma_f32_16x16x32_bf16 v[20:23], v[160:163], v[224:227], v[20:23]
	v_mfma_f32_16x16x32_bf16 v[16:19], v[190:193], v[224:227], v[16:19]
	v_mfma_f32_16x16x32_bf16 v[4:7], v[160:163], v[232:235], v[4:7]
	v_mfma_f32_16x16x32_bf16 v[0:3], v[190:193], v[232:235], v[0:3]
	v_mfma_f32_16x16x32_bf16 v[52:55], v[164:167], v[202:205], v[52:55]
	v_mfma_f32_16x16x32_bf16 v[48:51], v[194:197], v[202:205], v[48:51]
	v_mfma_f32_16x16x32_bf16 v[36:39], v[164:167], v[220:223], v[36:39]
	v_mfma_f32_16x16x32_bf16 v[32:35], v[194:197], v[220:223], v[32:35]
	v_mfma_f32_16x16x32_bf16 v[20:23], v[164:167], v[228:231], v[20:23]
	v_mfma_f32_16x16x32_bf16 v[16:19], v[194:197], v[228:231], v[16:19]
	v_mfma_f32_16x16x32_bf16 v[4:7], v[164:167], v[236:239], v[4:7]
	v_mfma_f32_16x16x32_bf16 v[0:3], v[194:197], v[236:239], v[0:3]
	s_setprio 0
	s_barrier
	s_add_i32 s58, 0, 0x18000
	s_add_i32 s59, 0, 0x1c000
	v_add_u32_e32 v156, s58, v141
	v_add_u32_e32 v170, s59, v141
	ds_read_b128 v[144:147], v156
	ds_read_b128 v[148:151], v156 offset:1024
	ds_read_b128 v[152:155], v156 offset:2048
	ds_read_b128 v[156:159], v156 offset:3072
	ds_read_b128 v[160:163], v170
	ds_read_b128 v[164:167], v170 offset:1024
	ds_read_b128 v[190:193], v170 offset:2048
	ds_read_b128 v[194:197], v170 offset:3072
	s_add_u32 s12, s18, 0x28000
	s_addc_u32 s13, s19, 0
	s_mov_b32 m0, s25
	v_lshl_add_u64 v[244:245], s[12:13], 0, v[134:135]
	ds_read_b128 v[198:201], v143 offset:32768
	ds_read_b128 v[202:205], v143 offset:33792
	ds_read_b128 v[206:209], v143 offset:34816
	ds_read_b128 v[220:223], v143 offset:35840
	ds_read_b128 v[224:227], v143 offset:36864
	ds_read_b128 v[228:231], v143 offset:37888
	ds_read_b128 v[232:235], v143 offset:38912
	ds_read_b128 v[236:239], v143 offset:39936
	global_load_lds_dwordx4 v[244:245], off
	v_lshl_add_u64 v[244:245], s[12:13], 0, v[130:131]
	s_mov_b32 m0, s26
	s_nop 0
	global_load_lds_dwordx4 v[244:245], off
	s_waitcnt vmcnt(8)
	s_waitcnt lgkmcnt(0)
	s_barrier
	s_setprio 1
	s_waitcnt lgkmcnt(0)
	v_mfma_f32_16x16x32_bf16 v[124:127], v[144:147], v[198:201], v[124:127]
	v_mfma_f32_16x16x32_bf16 v[120:123], v[152:155], v[198:201], v[120:123]
	v_mfma_f32_16x16x32_bf16 v[108:111], v[144:147], v[206:209], v[108:111]
	v_mfma_f32_16x16x32_bf16 v[104:107], v[152:155], v[206:209], v[104:107]
	v_mfma_f32_16x16x32_bf16 v[92:95], v[144:147], v[224:227], v[92:95]
	v_mfma_f32_16x16x32_bf16 v[88:91], v[152:155], v[224:227], v[88:91]
	v_mfma_f32_16x16x32_bf16 v[76:79], v[144:147], v[232:235], v[76:79]
	v_mfma_f32_16x16x32_bf16 v[72:75], v[152:155], v[232:235], v[72:75]
	v_mfma_f32_16x16x32_bf16 v[124:127], v[148:151], v[202:205], v[124:127]
	v_mfma_f32_16x16x32_bf16 v[120:123], v[156:159], v[202:205], v[120:123]
	v_mfma_f32_16x16x32_bf16 v[108:111], v[148:151], v[220:223], v[108:111]
	v_mfma_f32_16x16x32_bf16 v[104:107], v[156:159], v[220:223], v[104:107]
	v_mfma_f32_16x16x32_bf16 v[92:95], v[148:151], v[228:231], v[92:95]
	v_mfma_f32_16x16x32_bf16 v[88:91], v[156:159], v[228:231], v[88:91]
	v_mfma_f32_16x16x32_bf16 v[76:79], v[148:151], v[236:239], v[76:79]
	v_mfma_f32_16x16x32_bf16 v[72:75], v[156:159], v[236:239], v[72:75]
	s_setprio 0
	s_setprio 1
	v_mfma_f32_16x16x32_bf16 v[116:119], v[160:163], v[198:201], v[116:119]
	v_mfma_f32_16x16x32_bf16 v[112:115], v[190:193], v[198:201], v[112:115]
	v_mfma_f32_16x16x32_bf16 v[100:103], v[160:163], v[206:209], v[100:103]
	v_mfma_f32_16x16x32_bf16 v[96:99], v[190:193], v[206:209], v[96:99]
	v_mfma_f32_16x16x32_bf16 v[84:87], v[160:163], v[224:227], v[84:87]
	v_mfma_f32_16x16x32_bf16 v[80:83], v[190:193], v[224:227], v[80:83]
	v_mfma_f32_16x16x32_bf16 v[68:71], v[160:163], v[232:235], v[68:71]
	v_mfma_f32_16x16x32_bf16 v[64:67], v[190:193], v[232:235], v[64:67]
	v_mfma_f32_16x16x32_bf16 v[116:119], v[164:167], v[202:205], v[116:119]
	v_mfma_f32_16x16x32_bf16 v[112:115], v[194:197], v[202:205], v[112:115]
	v_mfma_f32_16x16x32_bf16 v[100:103], v[164:167], v[220:223], v[100:103]
	v_mfma_f32_16x16x32_bf16 v[96:99], v[194:197], v[220:223], v[96:99]
	v_mfma_f32_16x16x32_bf16 v[84:87], v[164:167], v[228:231], v[84:87]
	v_mfma_f32_16x16x32_bf16 v[80:83], v[194:197], v[228:231], v[80:83]
	v_mfma_f32_16x16x32_bf16 v[68:71], v[164:167], v[236:239], v[68:71]
	v_mfma_f32_16x16x32_bf16 v[64:67], v[194:197], v[236:239], v[64:67]
	s_setprio 0
	s_barrier
	s_add_i32 s12, s58, s22
	v_lshl_add_u64 v[178:179], v[178:179], 0, s[50:51]
	s_mov_b32 m0, s12
	ds_read_b128 v[198:201], v143 offset:49152
	ds_read_b128 v[202:205], v143 offset:50176
	ds_read_b128 v[206:209], v143 offset:51200
	ds_read_b128 v[220:223], v143 offset:52224
	ds_read_b128 v[224:227], v143 offset:53248
	ds_read_b128 v[228:231], v143 offset:54272
	ds_read_b128 v[232:235], v143 offset:55296
	ds_read_b128 v[236:239], v143 offset:56320
	global_load_lds_dwordx4 v[178:179], off
	s_add_i32 m0, s12, 0x2000
	s_add_u32 s12, s16, 0x28080
	v_lshl_add_u64 v[178:179], v[180:181], 0, s[50:51]
	s_addc_u32 s13, s17, 0
	s_add_i32 s16, s59, s22
	global_load_lds_dwordx4 v[178:179], off
	v_lshl_add_u64 v[178:179], s[12:13], 0, v[132:133]
	s_mov_b32 m0, s16
	s_nop 0
	global_load_lds_dwordx4 v[178:179], off
	v_lshl_add_u64 v[178:179], s[12:13], 0, v[128:129]
	s_add_i32 m0, s16, 0x2000
	s_nop 0
	global_load_lds_dwordx4 v[178:179], off
	v_lshl_add_u64 v[178:179], v[240:241], 0, s[50:51]
	s_mov_b32 m0, s27
	s_nop 0
	global_load_lds_dwordx4 v[178:179], off
	v_lshl_add_u64 v[178:179], v[242:243], 0, s[50:51]
	s_mov_b32 m0, s34
	s_nop 0
	global_load_lds_dwordx4 v[178:179], off
	s_waitcnt vmcnt(8)
	s_waitcnt lgkmcnt(0)
	s_barrier
	s_setprio 1
	s_waitcnt lgkmcnt(0)
	v_mfma_f32_16x16x32_bf16 v[60:63], v[144:147], v[198:201], v[60:63]
	v_mfma_f32_16x16x32_bf16 v[56:59], v[152:155], v[198:201], v[56:59]
	v_mfma_f32_16x16x32_bf16 v[44:47], v[144:147], v[206:209], v[44:47]
	v_mfma_f32_16x16x32_bf16 v[40:43], v[152:155], v[206:209], v[40:43]
	v_mfma_f32_16x16x32_bf16 v[28:31], v[144:147], v[224:227], v[28:31]
	v_mfma_f32_16x16x32_bf16 v[24:27], v[152:155], v[224:227], v[24:27]
	v_mfma_f32_16x16x32_bf16 v[12:15], v[144:147], v[232:235], v[12:15]
	v_mfma_f32_16x16x32_bf16 v[8:11], v[152:155], v[232:235], v[8:11]
	v_mfma_f32_16x16x32_bf16 v[60:63], v[148:151], v[202:205], v[60:63]
	v_mfma_f32_16x16x32_bf16 v[56:59], v[156:159], v[202:205], v[56:59]
	v_mfma_f32_16x16x32_bf16 v[44:47], v[148:151], v[220:223], v[44:47]
	v_mfma_f32_16x16x32_bf16 v[40:43], v[156:159], v[220:223], v[40:43]
	v_mfma_f32_16x16x32_bf16 v[28:31], v[148:151], v[228:231], v[28:31]
	v_mfma_f32_16x16x32_bf16 v[24:27], v[156:159], v[228:231], v[24:27]
	v_mfma_f32_16x16x32_bf16 v[12:15], v[148:151], v[236:239], v[12:15]
	v_mfma_f32_16x16x32_bf16 v[8:11], v[156:159], v[236:239], v[8:11]
	s_setprio 0
	s_setprio 1
	v_mfma_f32_16x16x32_bf16 v[52:55], v[160:163], v[198:201], v[52:55]
	v_mfma_f32_16x16x32_bf16 v[48:51], v[190:193], v[198:201], v[48:51]
	v_mfma_f32_16x16x32_bf16 v[36:39], v[160:163], v[206:209], v[36:39]
	v_mfma_f32_16x16x32_bf16 v[32:35], v[190:193], v[206:209], v[32:35]
	v_mfma_f32_16x16x32_bf16 v[20:23], v[160:163], v[224:227], v[20:23]
	v_mfma_f32_16x16x32_bf16 v[16:19], v[190:193], v[224:227], v[16:19]
	v_mfma_f32_16x16x32_bf16 v[4:7], v[160:163], v[232:235], v[4:7]
	v_mfma_f32_16x16x32_bf16 v[0:3], v[190:193], v[232:235], v[0:3]
	v_mfma_f32_16x16x32_bf16 v[52:55], v[164:167], v[202:205], v[52:55]
	v_mfma_f32_16x16x32_bf16 v[48:51], v[194:197], v[202:205], v[48:51]
	v_mfma_f32_16x16x32_bf16 v[36:39], v[164:167], v[220:223], v[36:39]
	v_mfma_f32_16x16x32_bf16 v[32:35], v[194:197], v[220:223], v[32:35]
	v_mfma_f32_16x16x32_bf16 v[20:23], v[164:167], v[228:231], v[20:23]
	v_mfma_f32_16x16x32_bf16 v[16:19], v[194:197], v[228:231], v[16:19]
	v_mfma_f32_16x16x32_bf16 v[4:7], v[164:167], v[236:239], v[4:7]
	v_mfma_f32_16x16x32_bf16 v[0:3], v[194:197], v[236:239], v[0:3]
	s_add_i32 s57, s57, 2
	s_add_u32 s55, s55, 0x100
	s_addc_u32 s56, s56, 0
	s_cmp_gt_u32 s57, 7
	s_mov_b64 s[12:13], s[14:15]
	s_setprio 0
	s_barrier
	s_cbranch_scc0 .LBB0_797
	s_and_b64 vcc, exec, s[6:7]
	s_cbranch_vccz .LBB0_800
	s_barrier

.LBB0_869:
	s_add_u32 s18, s16, 0xfffe0080
	s_addc_u32 s19, s17, -1
	s_add_i32 s60, 0, 0x10000
	s_cmp_eq_u32 s59, 4
	s_cselect_b32 s21, s11, s19
	s_cselect_b32 s20, s55, s18
	s_cselect_b32 s19, s9, s58
	s_cselect_b32 s18, s56, s57
	s_add_i32 s62, 0, 0x14000
	v_add_u32_e32 v52, s60, v206
	v_add_u32_e32 v148, s62, v206
	ds_read_b128 v[32:35], v52
	ds_read_b128 v[36:39], v52 offset:1024
	ds_read_b128 v[48:51], v52 offset:2048
	ds_read_b128 v[52:55], v52 offset:3072
	ds_read_b128 v[120:123], v148
	ds_read_b128 v[132:135], v148 offset:1024
	ds_read_b128 v[144:147], v148 offset:2048
	ds_read_b128 v[148:151], v148 offset:3072
	v_lshl_add_u64 v[178:179], s[16:17], 0, v[192:193]
	s_add_i32 m0, s25, 0xc000
	ds_read_b128 v[152:155], v208
	ds_read_b128 v[196:199], v208 offset:1024
	ds_read_b128 v[200:203], v208 offset:2048
	ds_read_b128 v[220:223], v208 offset:3072
	ds_read_b128 v[224:227], v208 offset:4096
	ds_read_b128 v[228:231], v208 offset:5120
	ds_read_b128 v[232:235], v208 offset:6144
	ds_read_b128 v[236:239], v208 offset:7168
	global_load_lds_dwordx4 v[178:179], off
	v_lshl_add_u64 v[178:179], s[16:17], 0, v[194:195]
	s_add_i32 m0, s25, 0xe000
	s_nop 0
	global_load_lds_dwordx4 v[178:179], off
	s_waitcnt vmcnt(8)
	s_waitcnt lgkmcnt(0)
	s_barrier
	s_setprio 1
	s_waitcnt lgkmcnt(0)
	v_mfma_f32_16x16x32_bf16 v[160:163], v[32:35], v[152:155], v[160:163]
	v_mfma_f32_16x16x32_bf16 v[156:159], v[48:51], v[152:155], v[156:159]
	v_mfma_f32_16x16x32_bf16 v[128:131], v[32:35], v[200:203], v[128:131]
	v_mfma_f32_16x16x32_bf16 v[124:127], v[48:51], v[200:203], v[124:127]
	v_mfma_f32_16x16x32_bf16 v[108:111], v[32:35], v[224:227], v[108:111]
	v_mfma_f32_16x16x32_bf16 v[104:107], v[48:51], v[224:227], v[104:107]
	v_mfma_f32_16x16x32_bf16 v[92:95], v[32:35], v[232:235], v[92:95]
	v_mfma_f32_16x16x32_bf16 v[88:91], v[48:51], v[232:235], v[88:91]
	v_mfma_f32_16x16x32_bf16 v[160:163], v[36:39], v[196:199], v[160:163]
	v_mfma_f32_16x16x32_bf16 v[156:159], v[52:55], v[196:199], v[156:159]
	v_mfma_f32_16x16x32_bf16 v[128:131], v[36:39], v[220:223], v[128:131]
	v_mfma_f32_16x16x32_bf16 v[124:127], v[52:55], v[220:223], v[124:127]
	v_mfma_f32_16x16x32_bf16 v[108:111], v[36:39], v[228:231], v[108:111]
	v_mfma_f32_16x16x32_bf16 v[104:107], v[52:55], v[228:231], v[104:107]
	v_mfma_f32_16x16x32_bf16 v[92:95], v[36:39], v[236:239], v[92:95]
	v_mfma_f32_16x16x32_bf16 v[88:91], v[52:55], v[236:239], v[88:91]
	s_setprio 0
	s_setprio 1
	v_mfma_f32_16x16x32_bf16 v[140:143], v[120:123], v[152:155], v[140:143]
	v_mfma_f32_16x16x32_bf16 v[136:139], v[144:147], v[152:155], v[136:139]
	v_mfma_f32_16x16x32_bf16 v[116:119], v[120:123], v[200:203], v[116:119]
	v_mfma_f32_16x16x32_bf16 v[112:115], v[144:147], v[200:203], v[112:115]
	v_mfma_f32_16x16x32_bf16 v[100:103], v[120:123], v[224:227], v[100:103]
	v_mfma_f32_16x16x32_bf16 v[96:99], v[144:147], v[224:227], v[96:99]
	v_mfma_f32_16x16x32_bf16 v[84:87], v[120:123], v[232:235], v[84:87]
	v_mfma_f32_16x16x32_bf16 v[80:83], v[144:147], v[232:235], v[80:83]
	v_mfma_f32_16x16x32_bf16 v[140:143], v[132:135], v[196:199], v[140:143]
	v_mfma_f32_16x16x32_bf16 v[136:139], v[148:151], v[196:199], v[136:139]
	v_mfma_f32_16x16x32_bf16 v[116:119], v[132:135], v[220:223], v[116:119]
	v_mfma_f32_16x16x32_bf16 v[112:115], v[148:151], v[220:223], v[112:115]
	v_mfma_f32_16x16x32_bf16 v[100:103], v[132:135], v[228:231], v[100:103]
	v_mfma_f32_16x16x32_bf16 v[96:99], v[148:151], v[228:231], v[96:99]
	v_mfma_f32_16x16x32_bf16 v[84:87], v[132:135], v[236:239], v[84:87]
	v_mfma_f32_16x16x32_bf16 v[80:83], v[148:151], v[236:239], v[80:83]
	s_setprio 0
	s_barrier
	s_add_i32 s60, s60, s24
	v_lshl_add_u64 v[178:179], s[18:19], 0, v[168:169]
	s_mov_b32 m0, s60
	ds_read_b128 v[152:155], v208 offset:16384
	ds_read_b128 v[196:199], v208 offset:17408
	ds_read_b128 v[200:203], v208 offset:18432
	ds_read_b128 v[220:223], v208 offset:19456
	ds_read_b128 v[224:227], v208 offset:20480
	ds_read_b128 v[228:231], v208 offset:21504
	ds_read_b128 v[232:235], v208 offset:22528
	ds_read_b128 v[236:239], v208 offset:23552
	global_load_lds_dwordx4 v[178:179], off
	s_add_i32 m0, s60, 0x2000
	s_add_u32 s60, s18, 0x20000
	v_lshl_add_u64 v[180:181], s[18:19], 0, v[164:165]
	s_addc_u32 s61, s19, 0
	s_add_i32 s62, s62, s24
	global_load_lds_dwordx4 v[180:181], off
	v_lshl_add_u64 v[204:205], s[60:61], 0, v[168:169]
	s_mov_b32 m0, s62
	v_lshl_add_u64 v[240:241], s[20:21], 0, v[166:167]
	global_load_lds_dwordx4 v[204:205], off
	v_lshl_add_u64 v[204:205], s[60:61], 0, v[164:165]
	s_add_i32 m0, s62, 0x2000
	s_nop 0
	global_load_lds_dwordx4 v[204:205], off
	v_lshl_add_u64 v[204:205], s[20:21], 0, v[190:191]
	s_mov_b32 m0, s25
	s_nop 0
	global_load_lds_dwordx4 v[204:205], off
	s_mov_b32 m0, s26
	s_nop 0
	global_load_lds_dwordx4 v[240:241], off
	s_waitcnt vmcnt(8)
	s_waitcnt lgkmcnt(0)
	s_barrier
	s_setprio 1
	s_waitcnt lgkmcnt(0)
	v_mfma_f32_16x16x32_bf16 v[76:79], v[32:35], v[152:155], v[76:79]
	v_mfma_f32_16x16x32_bf16 v[72:75], v[48:51], v[152:155], v[72:75]
	v_mfma_f32_16x16x32_bf16 v[60:63], v[32:35], v[200:203], v[60:63]
	v_mfma_f32_16x16x32_bf16 v[56:59], v[48:51], v[200:203], v[56:59]
	v_mfma_f32_16x16x32_bf16 v[28:31], v[32:35], v[224:227], v[28:31]
	v_mfma_f32_16x16x32_bf16 v[24:27], v[48:51], v[224:227], v[24:27]
	v_mfma_f32_16x16x32_bf16 v[12:15], v[32:35], v[232:235], v[12:15]
	v_mfma_f32_16x16x32_bf16 v[8:11], v[48:51], v[232:235], v[8:11]
	v_mfma_f32_16x16x32_bf16 v[76:79], v[36:39], v[196:199], v[76:79]
	v_mfma_f32_16x16x32_bf16 v[72:75], v[52:55], v[196:199], v[72:75]
	v_mfma_f32_16x16x32_bf16 v[60:63], v[36:39], v[220:223], v[60:63]
	v_mfma_f32_16x16x32_bf16 v[56:59], v[52:55], v[220:223], v[56:59]
	v_mfma_f32_16x16x32_bf16 v[28:31], v[36:39], v[228:231], v[28:31]
	v_mfma_f32_16x16x32_bf16 v[24:27], v[52:55], v[228:231], v[24:27]
	v_mfma_f32_16x16x32_bf16 v[12:15], v[36:39], v[236:239], v[12:15]
	v_mfma_f32_16x16x32_bf16 v[8:11], v[52:55], v[236:239], v[8:11]
	s_setprio 0
	s_setprio 1
	v_mfma_f32_16x16x32_bf16 v[44:47], v[120:123], v[200:203], v[44:47]
	v_mfma_f32_16x16x32_bf16 v[40:43], v[144:147], v[200:203], v[40:43]
	v_mfma_f32_16x16x32_bf16 v[20:23], v[120:123], v[224:227], v[20:23]
	v_mfma_f32_16x16x32_bf16 v[16:19], v[144:147], v[224:227], v[16:19]
	v_mfma_f32_16x16x32_bf16 v[4:7], v[120:123], v[232:235], v[4:7]
	v_mfma_f32_16x16x32_bf16 v[0:3], v[144:147], v[232:235], v[0:3]
	v_mfma_f32_16x16x32_bf16 v[32:35], v[120:123], v[152:155], v[68:71]
	v_mfma_f32_16x16x32_bf16 v[36:39], v[144:147], v[152:155], v[64:67]
	v_mfma_f32_16x16x32_bf16 v[44:47], v[132:135], v[220:223], v[44:47]
	v_mfma_f32_16x16x32_bf16 v[40:43], v[148:151], v[220:223], v[40:43]
	v_mfma_f32_16x16x32_bf16 v[20:23], v[132:135], v[228:231], v[20:23]
	v_mfma_f32_16x16x32_bf16 v[16:19], v[148:151], v[228:231], v[16:19]
	v_mfma_f32_16x16x32_bf16 v[4:7], v[132:135], v[236:239], v[4:7]
	v_mfma_f32_16x16x32_bf16 v[0:3], v[148:151], v[236:239], v[0:3]
	v_mfma_f32_16x16x32_bf16 v[32:35], v[132:135], v[196:199], v[32:35]
	v_mfma_f32_16x16x32_bf16 v[36:39], v[148:151], v[196:199], v[36:39]
	s_setprio 0
	s_barrier
	s_add_i32 s60, 0, 0x18000
	s_add_i32 s61, 0, 0x1c000
	v_add_u32_e32 v68, s60, v206
	v_add_u32_e32 v148, s61, v206
	ds_read_b128 v[48:51], v68
	ds_read_b128 v[52:55], v68 offset:1024
	ds_read_b128 v[64:67], v68 offset:2048
	ds_read_b128 v[68:71], v68 offset:3072
	ds_read_b128 v[120:123], v148
	ds_read_b128 v[132:135], v148 offset:1024
	ds_read_b128 v[144:147], v148 offset:2048
	ds_read_b128 v[148:151], v148 offset:3072
	s_add_u32 s20, s20, 0x20000
	s_addc_u32 s21, s21, 0
	s_mov_b32 m0, s27
	v_lshl_add_u64 v[242:243], s[20:21], 0, v[190:191]
	ds_read_b128 v[152:155], v208 offset:32768
	ds_read_b128 v[196:199], v208 offset:33792
	ds_read_b128 v[200:203], v208 offset:34816
	ds_read_b128 v[220:223], v208 offset:35840
	ds_read_b128 v[224:227], v208 offset:36864
	ds_read_b128 v[228:231], v208 offset:37888
	ds_read_b128 v[232:235], v208 offset:38912
	ds_read_b128 v[236:239], v208 offset:39936
	global_load_lds_dwordx4 v[242:243], off
	v_lshl_add_u64 v[242:243], s[20:21], 0, v[166:167]
	s_mov_b32 m0, s34
	s_nop 0
	global_load_lds_dwordx4 v[242:243], off
	s_waitcnt vmcnt(8)
	s_waitcnt lgkmcnt(0)
	s_barrier
	s_setprio 1
	s_waitcnt lgkmcnt(0)
	v_mfma_f32_16x16x32_bf16 v[160:163], v[48:51], v[152:155], v[160:163]
	v_mfma_f32_16x16x32_bf16 v[156:159], v[64:67], v[152:155], v[156:159]
	v_mfma_f32_16x16x32_bf16 v[128:131], v[48:51], v[200:203], v[128:131]
	v_mfma_f32_16x16x32_bf16 v[124:127], v[64:67], v[200:203], v[124:127]
	v_mfma_f32_16x16x32_bf16 v[108:111], v[48:51], v[224:227], v[108:111]
	v_mfma_f32_16x16x32_bf16 v[104:107], v[64:67], v[224:227], v[104:107]
	v_mfma_f32_16x16x32_bf16 v[92:95], v[48:51], v[232:235], v[92:95]
	v_mfma_f32_16x16x32_bf16 v[88:91], v[64:67], v[232:235], v[88:91]
	v_mfma_f32_16x16x32_bf16 v[160:163], v[52:55], v[196:199], v[160:163]
	v_mfma_f32_16x16x32_bf16 v[156:159], v[68:71], v[196:199], v[156:159]
	v_mfma_f32_16x16x32_bf16 v[128:131], v[52:55], v[220:223], v[128:131]
	v_mfma_f32_16x16x32_bf16 v[124:127], v[68:71], v[220:223], v[124:127]
	v_mfma_f32_16x16x32_bf16 v[108:111], v[52:55], v[228:231], v[108:111]
	v_mfma_f32_16x16x32_bf16 v[104:107], v[68:71], v[228:231], v[104:107]
	v_mfma_f32_16x16x32_bf16 v[92:95], v[52:55], v[236:239], v[92:95]
	v_mfma_f32_16x16x32_bf16 v[88:91], v[68:71], v[236:239], v[88:91]
	s_setprio 0
	s_setprio 1
	v_mfma_f32_16x16x32_bf16 v[140:143], v[120:123], v[152:155], v[140:143]
	v_mfma_f32_16x16x32_bf16 v[136:139], v[144:147], v[152:155], v[136:139]
	v_mfma_f32_16x16x32_bf16 v[116:119], v[120:123], v[200:203], v[116:119]
	v_mfma_f32_16x16x32_bf16 v[112:115], v[144:147], v[200:203], v[112:115]
	v_mfma_f32_16x16x32_bf16 v[100:103], v[120:123], v[224:227], v[100:103]
	v_mfma_f32_16x16x32_bf16 v[96:99], v[144:147], v[224:227], v[96:99]
	v_mfma_f32_16x16x32_bf16 v[84:87], v[120:123], v[232:235], v[84:87]
	v_mfma_f32_16x16x32_bf16 v[80:83], v[144:147], v[232:235], v[80:83]
	v_mfma_f32_16x16x32_bf16 v[140:143], v[132:135], v[196:199], v[140:143]
	v_mfma_f32_16x16x32_bf16 v[136:139], v[148:151], v[196:199], v[136:139]
	v_mfma_f32_16x16x32_bf16 v[116:119], v[132:135], v[220:223], v[116:119]
	v_mfma_f32_16x16x32_bf16 v[112:115], v[148:151], v[220:223], v[112:115]
	v_mfma_f32_16x16x32_bf16 v[100:103], v[132:135], v[228:231], v[100:103]
	v_mfma_f32_16x16x32_bf16 v[96:99], v[148:151], v[228:231], v[96:99]
	v_mfma_f32_16x16x32_bf16 v[84:87], v[132:135], v[236:239], v[84:87]
	v_mfma_f32_16x16x32_bf16 v[80:83], v[148:151], v[236:239], v[80:83]
	s_setprio 0
	s_barrier
	s_add_i32 s20, s60, s24
	v_lshl_add_u64 v[178:179], v[178:179], 0, s[50:51]
	s_mov_b32 m0, s20
	ds_read_b128 v[152:155], v208 offset:49152
	ds_read_b128 v[196:199], v208 offset:50176
	ds_read_b128 v[200:203], v208 offset:51200
	ds_read_b128 v[220:223], v208 offset:52224
	ds_read_b128 v[224:227], v208 offset:53248
	ds_read_b128 v[228:231], v208 offset:54272
	ds_read_b128 v[232:235], v208 offset:55296
	ds_read_b128 v[236:239], v208 offset:56320
	global_load_lds_dwordx4 v[178:179], off
	s_add_i32 m0, s20, 0x2000
	s_add_u32 s18, s18, 0x20080
	v_lshl_add_u64 v[178:179], v[180:181], 0, s[50:51]
	s_addc_u32 s19, s19, 0
	s_add_i32 s20, s61, s24
	global_load_lds_dwordx4 v[178:179], off
	v_lshl_add_u64 v[178:179], s[18:19], 0, v[168:169]
	s_mov_b32 m0, s20
	s_nop 0
	global_load_lds_dwordx4 v[178:179], off
	v_lshl_add_u64 v[178:179], s[18:19], 0, v[164:165]
	s_add_i32 m0, s20, 0x2000
	s_nop 0
	global_load_lds_dwordx4 v[178:179], off
	v_lshl_add_u64 v[178:179], v[204:205], 0, s[50:51]
	s_mov_b32 m0, s35
	s_nop 0
	global_load_lds_dwordx4 v[178:179], off
	v_lshl_add_u64 v[178:179], v[240:241], 0, s[50:51]
	s_mov_b32 m0, s86
	s_nop 0
	global_load_lds_dwordx4 v[178:179], off
	s_waitcnt vmcnt(8)
	s_waitcnt lgkmcnt(0)
	s_barrier
	s_setprio 1
	s_waitcnt lgkmcnt(0)
	v_mfma_f32_16x16x32_bf16 v[76:79], v[48:51], v[152:155], v[76:79]
	v_mfma_f32_16x16x32_bf16 v[72:75], v[64:67], v[152:155], v[72:75]
	v_mfma_f32_16x16x32_bf16 v[60:63], v[48:51], v[200:203], v[60:63]
	v_mfma_f32_16x16x32_bf16 v[56:59], v[64:67], v[200:203], v[56:59]
	v_mfma_f32_16x16x32_bf16 v[28:31], v[48:51], v[224:227], v[28:31]
	v_mfma_f32_16x16x32_bf16 v[24:27], v[64:67], v[224:227], v[24:27]
	v_mfma_f32_16x16x32_bf16 v[12:15], v[48:51], v[232:235], v[12:15]
	v_mfma_f32_16x16x32_bf16 v[8:11], v[64:67], v[232:235], v[8:11]
	v_mfma_f32_16x16x32_bf16 v[76:79], v[52:55], v[196:199], v[76:79]
	v_mfma_f32_16x16x32_bf16 v[72:75], v[68:71], v[196:199], v[72:75]
	v_mfma_f32_16x16x32_bf16 v[60:63], v[52:55], v[220:223], v[60:63]
	v_mfma_f32_16x16x32_bf16 v[56:59], v[68:71], v[220:223], v[56:59]
	v_mfma_f32_16x16x32_bf16 v[28:31], v[52:55], v[228:231], v[28:31]
	v_mfma_f32_16x16x32_bf16 v[24:27], v[68:71], v[228:231], v[24:27]
	v_mfma_f32_16x16x32_bf16 v[12:15], v[52:55], v[236:239], v[12:15]
	v_mfma_f32_16x16x32_bf16 v[8:11], v[68:71], v[236:239], v[8:11]
	s_setprio 0
	s_setprio 1
	v_mfma_f32_16x16x32_bf16 v[32:35], v[120:123], v[152:155], v[32:35]
	v_mfma_f32_16x16x32_bf16 v[68:71], v[132:135], v[196:199], v[32:35]
	v_mfma_f32_16x16x32_bf16 v[32:35], v[144:147], v[152:155], v[36:39]
	v_mfma_f32_16x16x32_bf16 v[64:67], v[148:151], v[196:199], v[32:35]
	v_mfma_f32_16x16x32_bf16 v[32:35], v[120:123], v[200:203], v[44:47]
	v_mfma_f32_16x16x32_bf16 v[44:47], v[132:135], v[220:223], v[32:35]
	v_mfma_f32_16x16x32_bf16 v[32:35], v[144:147], v[200:203], v[40:43]
	v_mfma_f32_16x16x32_bf16 v[20:23], v[120:123], v[224:227], v[20:23]
	v_mfma_f32_16x16x32_bf16 v[16:19], v[144:147], v[224:227], v[16:19]
	v_mfma_f32_16x16x32_bf16 v[4:7], v[120:123], v[232:235], v[4:7]
	v_mfma_f32_16x16x32_bf16 v[0:3], v[144:147], v[232:235], v[0:3]
	v_mfma_f32_16x16x32_bf16 v[40:43], v[148:151], v[220:223], v[32:35]
	v_mfma_f32_16x16x32_bf16 v[20:23], v[132:135], v[228:231], v[20:23]
	v_mfma_f32_16x16x32_bf16 v[16:19], v[148:151], v[228:231], v[16:19]
	v_mfma_f32_16x16x32_bf16 v[4:7], v[132:135], v[236:239], v[4:7]
	v_mfma_f32_16x16x32_bf16 v[0:3], v[148:151], v[236:239], v[0:3]
	s_add_i32 s59, s59, 2
	s_add_u32 s16, s16, 0x100
	s_addc_u32 s17, s17, 0
	s_add_u32 s57, s57, 0x100
	s_addc_u32 s58, s58, 0
	s_cmp_gt_u32 s59, 5
	s_setprio 0
	s_barrier
	s_cbranch_scc0 .LBB0_869
	s_and_b64 vcc, exec, s[6:7]
	s_mov_b64 s[56:57], s[44:45]
	s_mov_b32 s55, s72
	s_cbranch_vccz .LBB0_872
	s_barrier

.LBB0_980:
	s_add_u32 s18, s16, 0xfffc0080
	s_addc_u32 s19, s17, -1
	s_add_i32 s60, 0, 0x10000
	s_cmp_eq_u32 s90, 12
	s_cselect_b32 s21, s11, s19
	s_cselect_b32 s20, s57, s18
	s_cselect_b32 s19, s9, s87
	s_cselect_b32 s18, s58, s59
	s_add_i32 s62, 0, 0x14000
	v_add_u32_e32 v132, s60, v220
	v_add_u32_e32 v156, s62, v220
	ds_read_b128 v[120:123], v132
	ds_read_b128 v[124:127], v132 offset:1024
	ds_read_b128 v[128:131], v132 offset:2048
	ds_read_b128 v[132:135], v132 offset:3072
	ds_read_b128 v[136:139], v156
	ds_read_b128 v[140:143], v156 offset:1024
	ds_read_b128 v[148:151], v156 offset:2048
	ds_read_b128 v[156:159], v156 offset:3072
	v_lshl_add_u64 v[178:179], s[16:17], 0, v[196:197]
	s_add_i32 m0, s25, 0xc000
	ds_read_b128 v[160:163], v222
	ds_read_b128 v[164:167], v222 offset:1024
	ds_read_b128 v[200:203], v222 offset:2048
	ds_read_b128 v[204:207], v222 offset:3072
	ds_read_b128 v[224:227], v222 offset:4096
	ds_read_b128 v[228:231], v222 offset:5120
	ds_read_b128 v[232:235], v222 offset:6144
	ds_read_b128 v[236:239], v222 offset:7168
	global_load_lds_dwordx4 v[178:179], off
	v_lshl_add_u64 v[178:179], s[16:17], 0, v[198:199]
	s_add_i32 m0, s25, 0xe000
	s_nop 0
	global_load_lds_dwordx4 v[178:179], off
	s_waitcnt vmcnt(8)
	s_waitcnt lgkmcnt(0)
	s_barrier
	s_setprio 1
	s_waitcnt lgkmcnt(0)
	v_mfma_f32_16x16x32_bf16 v[152:155], v[120:123], v[160:163], v[152:155]
	v_mfma_f32_16x16x32_bf16 v[144:147], v[128:131], v[160:163], v[144:147]
	v_mfma_f32_16x16x32_bf16 v[108:111], v[120:123], v[200:203], v[108:111]
	v_mfma_f32_16x16x32_bf16 v[104:107], v[128:131], v[200:203], v[104:107]
	v_mfma_f32_16x16x32_bf16 v[92:95], v[120:123], v[224:227], v[92:95]
	v_mfma_f32_16x16x32_bf16 v[88:91], v[128:131], v[224:227], v[88:91]
	v_mfma_f32_16x16x32_bf16 v[76:79], v[120:123], v[232:235], v[76:79]
	v_mfma_f32_16x16x32_bf16 v[72:75], v[128:131], v[232:235], v[72:75]
	v_mfma_f32_16x16x32_bf16 v[152:155], v[124:127], v[164:167], v[152:155]
	v_mfma_f32_16x16x32_bf16 v[144:147], v[132:135], v[164:167], v[144:147]
	v_mfma_f32_16x16x32_bf16 v[108:111], v[124:127], v[204:207], v[108:111]
	v_mfma_f32_16x16x32_bf16 v[104:107], v[132:135], v[204:207], v[104:107]
	v_mfma_f32_16x16x32_bf16 v[92:95], v[124:127], v[228:231], v[92:95]
	v_mfma_f32_16x16x32_bf16 v[88:91], v[132:135], v[228:231], v[88:91]
	v_mfma_f32_16x16x32_bf16 v[76:79], v[124:127], v[236:239], v[76:79]
	v_mfma_f32_16x16x32_bf16 v[72:75], v[132:135], v[236:239], v[72:75]
	s_setprio 0
	s_setprio 1
	v_mfma_f32_16x16x32_bf16 v[116:119], v[136:139], v[160:163], v[116:119]
	v_mfma_f32_16x16x32_bf16 v[112:115], v[148:151], v[160:163], v[112:115]
	v_mfma_f32_16x16x32_bf16 v[100:103], v[136:139], v[200:203], v[100:103]
	v_mfma_f32_16x16x32_bf16 v[96:99], v[148:151], v[200:203], v[96:99]
	v_mfma_f32_16x16x32_bf16 v[84:87], v[136:139], v[224:227], v[84:87]
	v_mfma_f32_16x16x32_bf16 v[80:83], v[148:151], v[224:227], v[80:83]
	v_mfma_f32_16x16x32_bf16 v[68:71], v[136:139], v[232:235], v[68:71]
	v_mfma_f32_16x16x32_bf16 v[64:67], v[148:151], v[232:235], v[64:67]
	v_mfma_f32_16x16x32_bf16 v[116:119], v[140:143], v[164:167], v[116:119]
	v_mfma_f32_16x16x32_bf16 v[112:115], v[156:159], v[164:167], v[112:115]
	v_mfma_f32_16x16x32_bf16 v[100:103], v[140:143], v[204:207], v[100:103]
	v_mfma_f32_16x16x32_bf16 v[96:99], v[156:159], v[204:207], v[96:99]
	v_mfma_f32_16x16x32_bf16 v[84:87], v[140:143], v[228:231], v[84:87]
	v_mfma_f32_16x16x32_bf16 v[80:83], v[156:159], v[228:231], v[80:83]
	v_mfma_f32_16x16x32_bf16 v[68:71], v[140:143], v[236:239], v[68:71]
	v_mfma_f32_16x16x32_bf16 v[64:67], v[156:159], v[236:239], v[64:67]
	s_setprio 0
	s_barrier
	s_add_i32 s60, s60, s24
	v_lshl_add_u64 v[178:179], s[18:19], 0, v[168:169]
	s_mov_b32 m0, s60
	ds_read_b128 v[160:163], v222 offset:16384
	ds_read_b128 v[164:167], v222 offset:17408
	ds_read_b128 v[200:203], v222 offset:18432
	ds_read_b128 v[204:207], v222 offset:19456
	ds_read_b128 v[224:227], v222 offset:20480
	ds_read_b128 v[228:231], v222 offset:21504
	ds_read_b128 v[232:235], v222 offset:22528
	ds_read_b128 v[236:239], v222 offset:23552
	global_load_lds_dwordx4 v[178:179], off
	s_add_i32 m0, s60, 0x2000
	s_add_u32 s60, s18, 0x40000
	v_lshl_add_u64 v[180:181], s[18:19], 0, v[190:191]
	s_addc_u32 s61, s19, 0
	s_add_i32 s62, s62, s24
	global_load_lds_dwordx4 v[180:181], off
	v_lshl_add_u64 v[208:209], s[60:61], 0, v[168:169]
	s_mov_b32 m0, s62
	v_lshl_add_u64 v[240:241], s[20:21], 0, v[192:193]
	global_load_lds_dwordx4 v[208:209], off
	v_lshl_add_u64 v[208:209], s[60:61], 0, v[190:191]
	s_add_i32 m0, s62, 0x2000
	s_nop 0
	global_load_lds_dwordx4 v[208:209], off
	v_lshl_add_u64 v[208:209], s[20:21], 0, v[194:195]
	s_mov_b32 m0, s25
	s_nop 0
	global_load_lds_dwordx4 v[208:209], off
	s_mov_b32 m0, s26
	s_nop 0
	global_load_lds_dwordx4 v[240:241], off
	s_waitcnt vmcnt(8)
	s_waitcnt lgkmcnt(0)
	s_barrier
	s_setprio 1
	s_waitcnt lgkmcnt(0)
	v_mfma_f32_16x16x32_bf16 v[60:63], v[120:123], v[160:163], v[60:63]
	v_mfma_f32_16x16x32_bf16 v[56:59], v[128:131], v[160:163], v[56:59]
	v_mfma_f32_16x16x32_bf16 v[44:47], v[120:123], v[200:203], v[44:47]
	v_mfma_f32_16x16x32_bf16 v[40:43], v[128:131], v[200:203], v[40:43]
	v_mfma_f32_16x16x32_bf16 v[28:31], v[120:123], v[224:227], v[28:31]
	v_mfma_f32_16x16x32_bf16 v[24:27], v[128:131], v[224:227], v[24:27]
	v_mfma_f32_16x16x32_bf16 v[12:15], v[120:123], v[232:235], v[12:15]
	v_mfma_f32_16x16x32_bf16 v[8:11], v[128:131], v[232:235], v[8:11]
	v_mfma_f32_16x16x32_bf16 v[60:63], v[124:127], v[164:167], v[60:63]
	v_mfma_f32_16x16x32_bf16 v[56:59], v[132:135], v[164:167], v[56:59]
	v_mfma_f32_16x16x32_bf16 v[44:47], v[124:127], v[204:207], v[44:47]
	v_mfma_f32_16x16x32_bf16 v[40:43], v[132:135], v[204:207], v[40:43]
	v_mfma_f32_16x16x32_bf16 v[28:31], v[124:127], v[228:231], v[28:31]
	v_mfma_f32_16x16x32_bf16 v[24:27], v[132:135], v[228:231], v[24:27]
	v_mfma_f32_16x16x32_bf16 v[12:15], v[124:127], v[236:239], v[12:15]
	v_mfma_f32_16x16x32_bf16 v[8:11], v[132:135], v[236:239], v[8:11]
	s_setprio 0
	s_setprio 1
	v_mfma_f32_16x16x32_bf16 v[52:55], v[136:139], v[160:163], v[52:55]
	v_mfma_f32_16x16x32_bf16 v[48:51], v[148:151], v[160:163], v[48:51]
	v_mfma_f32_16x16x32_bf16 v[36:39], v[136:139], v[200:203], v[36:39]
	v_mfma_f32_16x16x32_bf16 v[32:35], v[148:151], v[200:203], v[32:35]
	v_mfma_f32_16x16x32_bf16 v[20:23], v[136:139], v[224:227], v[20:23]
	v_mfma_f32_16x16x32_bf16 v[16:19], v[148:151], v[224:227], v[16:19]
	v_mfma_f32_16x16x32_bf16 v[4:7], v[136:139], v[232:235], v[4:7]
	v_mfma_f32_16x16x32_bf16 v[0:3], v[148:151], v[232:235], v[0:3]
	v_mfma_f32_16x16x32_bf16 v[52:55], v[140:143], v[164:167], v[52:55]
	v_mfma_f32_16x16x32_bf16 v[48:51], v[156:159], v[164:167], v[48:51]
	v_mfma_f32_16x16x32_bf16 v[36:39], v[140:143], v[204:207], v[36:39]
	v_mfma_f32_16x16x32_bf16 v[32:35], v[156:159], v[204:207], v[32:35]
	v_mfma_f32_16x16x32_bf16 v[20:23], v[140:143], v[228:231], v[20:23]
	v_mfma_f32_16x16x32_bf16 v[16:19], v[156:159], v[228:231], v[16:19]
	v_mfma_f32_16x16x32_bf16 v[4:7], v[140:143], v[236:239], v[4:7]
	v_mfma_f32_16x16x32_bf16 v[0:3], v[156:159], v[236:239], v[0:3]
	s_setprio 0
	s_barrier
	s_add_i32 s60, 0, 0x18000
	s_add_i32 s61, 0, 0x1c000
	v_add_u32_e32 v132, s60, v220
	v_add_u32_e32 v156, s61, v220
	ds_read_b128 v[120:123], v132
	ds_read_b128 v[124:127], v132 offset:1024
	ds_read_b128 v[128:131], v132 offset:2048
	ds_read_b128 v[132:135], v132 offset:3072
	ds_read_b128 v[136:139], v156
	ds_read_b128 v[140:143], v156 offset:1024
	ds_read_b128 v[148:151], v156 offset:2048
	ds_read_b128 v[156:159], v156 offset:3072
	s_add_u32 s20, s20, 0x40000
	s_addc_u32 s21, s21, 0
	s_mov_b32 m0, s27
	v_lshl_add_u64 v[242:243], s[20:21], 0, v[194:195]
	ds_read_b128 v[160:163], v222 offset:32768
	ds_read_b128 v[164:167], v222 offset:33792
	ds_read_b128 v[200:203], v222 offset:34816
	ds_read_b128 v[204:207], v222 offset:35840
	ds_read_b128 v[224:227], v222 offset:36864
	ds_read_b128 v[228:231], v222 offset:37888
	ds_read_b128 v[232:235], v222 offset:38912
	ds_read_b128 v[236:239], v222 offset:39936
	global_load_lds_dwordx4 v[242:243], off
	v_lshl_add_u64 v[242:243], s[20:21], 0, v[192:193]
	s_mov_b32 m0, s34
	s_nop 0
	global_load_lds_dwordx4 v[242:243], off
	s_waitcnt vmcnt(8)
	s_waitcnt lgkmcnt(0)
	s_barrier
	s_setprio 1
	s_waitcnt lgkmcnt(0)
	v_mfma_f32_16x16x32_bf16 v[152:155], v[120:123], v[160:163], v[152:155]
	v_mfma_f32_16x16x32_bf16 v[144:147], v[128:131], v[160:163], v[144:147]
	v_mfma_f32_16x16x32_bf16 v[108:111], v[120:123], v[200:203], v[108:111]
	v_mfma_f32_16x16x32_bf16 v[104:107], v[128:131], v[200:203], v[104:107]
	v_mfma_f32_16x16x32_bf16 v[92:95], v[120:123], v[224:227], v[92:95]
	v_mfma_f32_16x16x32_bf16 v[88:91], v[128:131], v[224:227], v[88:91]
	v_mfma_f32_16x16x32_bf16 v[76:79], v[120:123], v[232:235], v[76:79]
	v_mfma_f32_16x16x32_bf16 v[72:75], v[128:131], v[232:235], v[72:75]
	v_mfma_f32_16x16x32_bf16 v[152:155], v[124:127], v[164:167], v[152:155]
	v_mfma_f32_16x16x32_bf16 v[144:147], v[132:135], v[164:167], v[144:147]
	v_mfma_f32_16x16x32_bf16 v[108:111], v[124:127], v[204:207], v[108:111]
	v_mfma_f32_16x16x32_bf16 v[104:107], v[132:135], v[204:207], v[104:107]
	v_mfma_f32_16x16x32_bf16 v[92:95], v[124:127], v[228:231], v[92:95]
	v_mfma_f32_16x16x32_bf16 v[88:91], v[132:135], v[228:231], v[88:91]
	v_mfma_f32_16x16x32_bf16 v[76:79], v[124:127], v[236:239], v[76:79]
	v_mfma_f32_16x16x32_bf16 v[72:75], v[132:135], v[236:239], v[72:75]
	s_setprio 0
	s_setprio 1
	v_mfma_f32_16x16x32_bf16 v[116:119], v[136:139], v[160:163], v[116:119]
	v_mfma_f32_16x16x32_bf16 v[112:115], v[148:151], v[160:163], v[112:115]
	v_mfma_f32_16x16x32_bf16 v[100:103], v[136:139], v[200:203], v[100:103]
	v_mfma_f32_16x16x32_bf16 v[96:99], v[148:151], v[200:203], v[96:99]
	v_mfma_f32_16x16x32_bf16 v[84:87], v[136:139], v[224:227], v[84:87]
	v_mfma_f32_16x16x32_bf16 v[80:83], v[148:151], v[224:227], v[80:83]
	v_mfma_f32_16x16x32_bf16 v[68:71], v[136:139], v[232:235], v[68:71]
	v_mfma_f32_16x16x32_bf16 v[64:67], v[148:151], v[232:235], v[64:67]
	v_mfma_f32_16x16x32_bf16 v[116:119], v[140:143], v[164:167], v[116:119]
	v_mfma_f32_16x16x32_bf16 v[112:115], v[156:159], v[164:167], v[112:115]
	v_mfma_f32_16x16x32_bf16 v[100:103], v[140:143], v[204:207], v[100:103]
	v_mfma_f32_16x16x32_bf16 v[96:99], v[156:159], v[204:207], v[96:99]
	v_mfma_f32_16x16x32_bf16 v[84:87], v[140:143], v[228:231], v[84:87]
	v_mfma_f32_16x16x32_bf16 v[80:83], v[156:159], v[228:231], v[80:83]
	v_mfma_f32_16x16x32_bf16 v[68:71], v[140:143], v[236:239], v[68:71]
	v_mfma_f32_16x16x32_bf16 v[64:67], v[156:159], v[236:239], v[64:67]
	s_setprio 0
	s_barrier
	s_add_i32 s20, s60, s24
	v_lshl_add_u64 v[178:179], v[178:179], 0, s[50:51]
	s_mov_b32 m0, s20
	ds_read_b128 v[160:163], v222 offset:49152
	ds_read_b128 v[164:167], v222 offset:50176
	ds_read_b128 v[200:203], v222 offset:51200
	ds_read_b128 v[204:207], v222 offset:52224
	ds_read_b128 v[224:227], v222 offset:53248
	ds_read_b128 v[228:231], v222 offset:54272
	ds_read_b128 v[232:235], v222 offset:55296
	ds_read_b128 v[236:239], v222 offset:56320
	global_load_lds_dwordx4 v[178:179], off
	s_add_i32 m0, s20, 0x2000
	s_add_u32 s18, s18, 0x40080
	v_lshl_add_u64 v[178:179], v[180:181], 0, s[50:51]
	s_addc_u32 s19, s19, 0
	s_add_i32 s20, s61, s24
	global_load_lds_dwordx4 v[178:179], off
	v_lshl_add_u64 v[178:179], s[18:19], 0, v[168:169]
	s_mov_b32 m0, s20
	s_nop 0
	global_load_lds_dwordx4 v[178:179], off
	v_lshl_add_u64 v[178:179], s[18:19], 0, v[190:191]
	s_add_i32 m0, s20, 0x2000
	s_nop 0
	global_load_lds_dwordx4 v[178:179], off
	v_lshl_add_u64 v[178:179], v[208:209], 0, s[50:51]
	s_mov_b32 m0, s36
	s_nop 0
	global_load_lds_dwordx4 v[178:179], off
	v_lshl_add_u64 v[178:179], v[240:241], 0, s[50:51]
	s_mov_b32 m0, s86
	s_nop 0
	global_load_lds_dwordx4 v[178:179], off
	s_waitcnt vmcnt(8)
	s_waitcnt lgkmcnt(0)
	s_barrier
	s_setprio 1
	s_waitcnt lgkmcnt(0)
	v_mfma_f32_16x16x32_bf16 v[60:63], v[120:123], v[160:163], v[60:63]
	v_mfma_f32_16x16x32_bf16 v[56:59], v[128:131], v[160:163], v[56:59]
	v_mfma_f32_16x16x32_bf16 v[44:47], v[120:123], v[200:203], v[44:47]
	v_mfma_f32_16x16x32_bf16 v[40:43], v[128:131], v[200:203], v[40:43]
	v_mfma_f32_16x16x32_bf16 v[28:31], v[120:123], v[224:227], v[28:31]
	v_mfma_f32_16x16x32_bf16 v[24:27], v[128:131], v[224:227], v[24:27]
	v_mfma_f32_16x16x32_bf16 v[12:15], v[120:123], v[232:235], v[12:15]
	v_mfma_f32_16x16x32_bf16 v[8:11], v[128:131], v[232:235], v[8:11]
	v_mfma_f32_16x16x32_bf16 v[60:63], v[124:127], v[164:167], v[60:63]
	v_mfma_f32_16x16x32_bf16 v[56:59], v[132:135], v[164:167], v[56:59]
	v_mfma_f32_16x16x32_bf16 v[44:47], v[124:127], v[204:207], v[44:47]
	v_mfma_f32_16x16x32_bf16 v[40:43], v[132:135], v[204:207], v[40:43]
	v_mfma_f32_16x16x32_bf16 v[28:31], v[124:127], v[228:231], v[28:31]
	v_mfma_f32_16x16x32_bf16 v[24:27], v[132:135], v[228:231], v[24:27]
	v_mfma_f32_16x16x32_bf16 v[12:15], v[124:127], v[236:239], v[12:15]
	v_mfma_f32_16x16x32_bf16 v[8:11], v[132:135], v[236:239], v[8:11]
	s_setprio 0
	s_setprio 1
	v_mfma_f32_16x16x32_bf16 v[52:55], v[136:139], v[160:163], v[52:55]
	v_mfma_f32_16x16x32_bf16 v[48:51], v[148:151], v[160:163], v[48:51]
	v_mfma_f32_16x16x32_bf16 v[36:39], v[136:139], v[200:203], v[36:39]
	v_mfma_f32_16x16x32_bf16 v[32:35], v[148:151], v[200:203], v[32:35]
	v_mfma_f32_16x16x32_bf16 v[20:23], v[136:139], v[224:227], v[20:23]
	v_mfma_f32_16x16x32_bf16 v[16:19], v[148:151], v[224:227], v[16:19]
	v_mfma_f32_16x16x32_bf16 v[4:7], v[136:139], v[232:235], v[4:7]
	v_mfma_f32_16x16x32_bf16 v[0:3], v[148:151], v[232:235], v[0:3]
	v_mfma_f32_16x16x32_bf16 v[52:55], v[140:143], v[164:167], v[52:55]
	v_mfma_f32_16x16x32_bf16 v[48:51], v[156:159], v[164:167], v[48:51]
	v_mfma_f32_16x16x32_bf16 v[36:39], v[140:143], v[204:207], v[36:39]
	v_mfma_f32_16x16x32_bf16 v[32:35], v[156:159], v[204:207], v[32:35]
	v_mfma_f32_16x16x32_bf16 v[20:23], v[140:143], v[228:231], v[20:23]
	v_mfma_f32_16x16x32_bf16 v[16:19], v[156:159], v[228:231], v[16:19]
	v_mfma_f32_16x16x32_bf16 v[4:7], v[140:143], v[236:239], v[4:7]
	v_mfma_f32_16x16x32_bf16 v[0:3], v[156:159], v[236:239], v[0:3]
	s_add_i32 s90, s90, 2
	s_add_u32 s16, s16, 0x100
	s_addc_u32 s17, s17, 0
	s_add_u32 s59, s59, 0x100
	s_addc_u32 s87, s87, 0
	s_cmp_gt_u32 s90, 13
	s_setprio 0
	s_barrier
	s_cbranch_scc0 .LBB0_980
	s_and_b64 vcc, exec, s[6:7]
	s_cbranch_vccz .LBB0_983
	s_barrier

.LBB0_1065:
	s_add_u32 s16, s0, 0xfffc0080
	s_addc_u32 s17, s1, -1
	s_add_i32 s60, 0, 0x10000
	s_cmp_eq_u32 s59, 12
	s_cselect_b32 s19, s11, s17
	s_cselect_b32 s18, s55, s16
	v_add_u32_e32 v145, s60, v161
	s_cselect_b32 s17, s9, s58
	s_cselect_b32 s16, s56, s57
	s_add_i32 s62, 0, 0x14000
	ds_read_b128 v[146:149], v145
	ds_read_b128 v[150:153], v145 offset:1024
	ds_read_b128 v[190:193], v145 offset:2048
	ds_read_b128 v[194:197], v145 offset:3072
	v_add_u32_e32 v145, s62, v161
	ds_read_b128 v[198:201], v145
	ds_read_b128 v[202:205], v145 offset:1024
	ds_read_b128 v[206:209], v145 offset:2048
	ds_read_b128 v[220:223], v145 offset:3072
	v_lshl_add_u64 v[154:155], s[0:1], 0, v[140:141]
	s_add_i32 m0, s23, 0xc000
	ds_read_b128 v[224:227], v164
	ds_read_b128 v[228:231], v164 offset:1024
	ds_read_b128 v[232:235], v164 offset:2048
	ds_read_b128 v[236:239], v164 offset:3072
	ds_read_b128 v[240:243], v164 offset:4096
	ds_read_b128 v[244:247], v164 offset:5120
	ds_read_b128 v[248:251], v164 offset:6144
	ds_read_b128 v[178:181], v164 offset:7168
	global_load_lds_dwordx4 v[154:155], off
	v_lshl_add_u64 v[154:155], s[0:1], 0, v[142:143]
	s_add_i32 m0, s23, 0xe000
	s_nop 0
	global_load_lds_dwordx4 v[154:155], off
	s_waitcnt vmcnt(8)
	s_waitcnt lgkmcnt(0)
	s_barrier
	s_setprio 1
	s_waitcnt lgkmcnt(0)
	v_mfma_f32_16x16x32_bf16 v[124:127], v[146:149], v[224:227], v[124:127]
	v_mfma_f32_16x16x32_bf16 v[116:119], v[190:193], v[224:227], v[116:119]
	v_mfma_f32_16x16x32_bf16 v[108:111], v[146:149], v[232:235], v[108:111]
	v_mfma_f32_16x16x32_bf16 v[100:103], v[190:193], v[232:235], v[100:103]
	v_mfma_f32_16x16x32_bf16 v[92:95], v[146:149], v[240:243], v[92:95]
	v_mfma_f32_16x16x32_bf16 v[84:87], v[190:193], v[240:243], v[84:87]
	v_mfma_f32_16x16x32_bf16 v[76:79], v[146:149], v[248:251], v[76:79]
	v_mfma_f32_16x16x32_bf16 v[68:71], v[190:193], v[248:251], v[68:71]
	v_mfma_f32_16x16x32_bf16 v[124:127], v[150:153], v[228:231], v[124:127]
	v_mfma_f32_16x16x32_bf16 v[116:119], v[194:197], v[228:231], v[116:119]
	v_mfma_f32_16x16x32_bf16 v[108:111], v[150:153], v[236:239], v[108:111]
	v_mfma_f32_16x16x32_bf16 v[100:103], v[194:197], v[236:239], v[100:103]
	v_mfma_f32_16x16x32_bf16 v[92:95], v[150:153], v[244:247], v[92:95]
	v_mfma_f32_16x16x32_bf16 v[84:87], v[194:197], v[244:247], v[84:87]
	v_mfma_f32_16x16x32_bf16 v[76:79], v[150:153], v[178:181], v[76:79]
	v_mfma_f32_16x16x32_bf16 v[68:71], v[194:197], v[178:181], v[68:71]
	s_setprio 0
	s_setprio 1
	v_mfma_f32_16x16x32_bf16 v[120:123], v[198:201], v[224:227], v[120:123]
	v_mfma_f32_16x16x32_bf16 v[112:115], v[206:209], v[224:227], v[112:115]
	v_mfma_f32_16x16x32_bf16 v[104:107], v[198:201], v[232:235], v[104:107]
	v_mfma_f32_16x16x32_bf16 v[96:99], v[206:209], v[232:235], v[96:99]
	v_mfma_f32_16x16x32_bf16 v[88:91], v[198:201], v[240:243], v[88:91]
	v_mfma_f32_16x16x32_bf16 v[80:83], v[206:209], v[240:243], v[80:83]
	v_mfma_f32_16x16x32_bf16 v[72:75], v[198:201], v[248:251], v[72:75]
	v_mfma_f32_16x16x32_bf16 v[64:67], v[206:209], v[248:251], v[64:67]
	v_mfma_f32_16x16x32_bf16 v[120:123], v[202:205], v[228:231], v[120:123]
	v_mfma_f32_16x16x32_bf16 v[112:115], v[220:223], v[228:231], v[112:115]
	v_mfma_f32_16x16x32_bf16 v[104:107], v[202:205], v[236:239], v[104:107]
	v_mfma_f32_16x16x32_bf16 v[96:99], v[220:223], v[236:239], v[96:99]
	v_mfma_f32_16x16x32_bf16 v[88:91], v[202:205], v[244:247], v[88:91]
	v_mfma_f32_16x16x32_bf16 v[80:83], v[220:223], v[244:247], v[80:83]
	v_mfma_f32_16x16x32_bf16 v[72:75], v[202:205], v[178:181], v[72:75]
	v_mfma_f32_16x16x32_bf16 v[64:67], v[220:223], v[178:181], v[64:67]
	s_setprio 0
	s_barrier
	s_add_i32 s60, s60, s22
	v_lshl_add_u64 v[154:155], s[16:17], 0, v[132:133]
	s_mov_b32 m0, s60
	ds_read_b128 v[178:181], v164 offset:16384
	ds_read_b128 v[224:227], v164 offset:17408
	ds_read_b128 v[228:231], v164 offset:18432
	ds_read_b128 v[232:235], v164 offset:19456
	ds_read_b128 v[236:239], v164 offset:20480
	ds_read_b128 v[240:243], v164 offset:21504
	ds_read_b128 v[244:247], v164 offset:22528
	ds_read_b128 v[248:251], v164 offset:23552
	global_load_lds_dwordx4 v[154:155], off
	s_add_i32 m0, s60, 0x2000
	s_add_u32 s60, s16, 0x40000
	v_lshl_add_u64 v[158:159], s[16:17], 0, v[128:129]
	s_addc_u32 s61, s17, 0
	s_add_i32 s62, s62, s22
	global_load_lds_dwordx4 v[158:159], off
	v_lshl_add_u64 v[162:163], s[60:61], 0, v[132:133]
	s_mov_b32 m0, s62
	v_lshl_add_u64 v[166:167], s[18:19], 0, v[130:131]
	global_load_lds_dwordx4 v[162:163], off
	v_lshl_add_u64 v[162:163], s[60:61], 0, v[128:129]
	s_add_i32 m0, s62, 0x2000
	s_nop 0
	global_load_lds_dwordx4 v[162:163], off
	v_lshl_add_u64 v[162:163], s[18:19], 0, v[134:135]
	s_mov_b32 m0, s23
	s_nop 0
	global_load_lds_dwordx4 v[162:163], off
	s_mov_b32 m0, s24
	s_nop 0
	global_load_lds_dwordx4 v[166:167], off
	s_waitcnt vmcnt(8)
	s_waitcnt lgkmcnt(0)
	s_barrier
	s_setprio 1
	s_waitcnt lgkmcnt(0)
	v_mfma_f32_16x16x32_bf16 v[60:63], v[146:149], v[178:181], v[60:63]
	v_mfma_f32_16x16x32_bf16 v[52:55], v[190:193], v[178:181], v[52:55]
	v_mfma_f32_16x16x32_bf16 v[44:47], v[146:149], v[228:231], v[44:47]
	v_mfma_f32_16x16x32_bf16 v[36:39], v[190:193], v[228:231], v[36:39]
	v_mfma_f32_16x16x32_bf16 v[28:31], v[146:149], v[236:239], v[28:31]
	v_mfma_f32_16x16x32_bf16 v[20:23], v[190:193], v[236:239], v[20:23]
	v_mfma_f32_16x16x32_bf16 v[12:15], v[146:149], v[244:247], v[12:15]
	v_mfma_f32_16x16x32_bf16 v[4:7], v[190:193], v[244:247], v[4:7]
	v_mfma_f32_16x16x32_bf16 v[60:63], v[150:153], v[224:227], v[60:63]
	v_mfma_f32_16x16x32_bf16 v[52:55], v[194:197], v[224:227], v[52:55]
	v_mfma_f32_16x16x32_bf16 v[44:47], v[150:153], v[232:235], v[44:47]
	v_mfma_f32_16x16x32_bf16 v[36:39], v[194:197], v[232:235], v[36:39]
	v_mfma_f32_16x16x32_bf16 v[28:31], v[150:153], v[240:243], v[28:31]
	v_mfma_f32_16x16x32_bf16 v[20:23], v[194:197], v[240:243], v[20:23]
	v_mfma_f32_16x16x32_bf16 v[12:15], v[150:153], v[248:251], v[12:15]
	v_mfma_f32_16x16x32_bf16 v[4:7], v[194:197], v[248:251], v[4:7]
	s_setprio 0
	s_setprio 1
	v_mfma_f32_16x16x32_bf16 v[56:59], v[198:201], v[178:181], v[56:59]
	v_mfma_f32_16x16x32_bf16 v[48:51], v[206:209], v[178:181], v[48:51]
	v_mfma_f32_16x16x32_bf16 v[40:43], v[198:201], v[228:231], v[40:43]
	v_mfma_f32_16x16x32_bf16 v[32:35], v[206:209], v[228:231], v[32:35]
	v_mfma_f32_16x16x32_bf16 v[24:27], v[198:201], v[236:239], v[24:27]
	v_mfma_f32_16x16x32_bf16 v[16:19], v[206:209], v[236:239], v[16:19]
	v_mfma_f32_16x16x32_bf16 v[8:11], v[198:201], v[244:247], v[8:11]
	v_mfma_f32_16x16x32_bf16 v[0:3], v[206:209], v[244:247], v[0:3]
	v_mfma_f32_16x16x32_bf16 v[56:59], v[202:205], v[224:227], v[56:59]
	v_mfma_f32_16x16x32_bf16 v[48:51], v[220:223], v[224:227], v[48:51]
	v_mfma_f32_16x16x32_bf16 v[40:43], v[202:205], v[232:235], v[40:43]
	v_mfma_f32_16x16x32_bf16 v[32:35], v[220:223], v[232:235], v[32:35]
	v_mfma_f32_16x16x32_bf16 v[24:27], v[202:205], v[240:243], v[24:27]
	v_mfma_f32_16x16x32_bf16 v[16:19], v[220:223], v[240:243], v[16:19]
	v_mfma_f32_16x16x32_bf16 v[8:11], v[202:205], v[248:251], v[8:11]
	v_mfma_f32_16x16x32_bf16 v[0:3], v[220:223], v[248:251], v[0:3]
	s_setprio 0
	s_barrier
	s_add_i32 s60, 0, 0x18000
	v_add_u32_e32 v145, s60, v161
	s_add_i32 s61, 0, 0x1c000
	ds_read_b128 v[146:149], v145
	ds_read_b128 v[150:153], v145 offset:1024
	ds_read_b128 v[178:181], v145 offset:2048
	ds_read_b128 v[190:193], v145 offset:3072
	v_add_u32_e32 v145, s61, v161
	ds_read_b128 v[194:197], v145
	ds_read_b128 v[198:201], v145 offset:1024
	ds_read_b128 v[202:205], v145 offset:2048
	ds_read_b128 v[206:209], v145 offset:3072
	s_add_u32 s18, s18, 0x40000
	s_addc_u32 s19, s19, 0
	s_mov_b32 m0, s25
	v_lshl_add_u64 v[214:215], s[18:19], 0, v[134:135]
	ds_read_b128 v[220:223], v164 offset:32768
	ds_read_b128 v[224:227], v164 offset:33792
	ds_read_b128 v[228:231], v164 offset:34816
	ds_read_b128 v[232:235], v164 offset:35840
	ds_read_b128 v[236:239], v164 offset:36864
	ds_read_b128 v[240:243], v164 offset:37888
	ds_read_b128 v[244:247], v164 offset:38912
	ds_read_b128 v[248:251], v164 offset:39936
	global_load_lds_dwordx4 v[214:215], off
	v_lshl_add_u64 v[214:215], s[18:19], 0, v[130:131]
	s_mov_b32 m0, s26
	s_nop 0
	global_load_lds_dwordx4 v[214:215], off
	s_waitcnt vmcnt(8)
	s_waitcnt lgkmcnt(0)
	s_barrier
	s_setprio 1
	s_waitcnt lgkmcnt(0)
	v_mfma_f32_16x16x32_bf16 v[124:127], v[146:149], v[220:223], v[124:127]
	v_mfma_f32_16x16x32_bf16 v[116:119], v[178:181], v[220:223], v[116:119]
	v_mfma_f32_16x16x32_bf16 v[108:111], v[146:149], v[228:231], v[108:111]
	v_mfma_f32_16x16x32_bf16 v[100:103], v[178:181], v[228:231], v[100:103]
	v_mfma_f32_16x16x32_bf16 v[92:95], v[146:149], v[236:239], v[92:95]
	v_mfma_f32_16x16x32_bf16 v[84:87], v[178:181], v[236:239], v[84:87]
	v_mfma_f32_16x16x32_bf16 v[76:79], v[146:149], v[244:247], v[76:79]
	v_mfma_f32_16x16x32_bf16 v[68:71], v[178:181], v[244:247], v[68:71]
	v_mfma_f32_16x16x32_bf16 v[124:127], v[150:153], v[224:227], v[124:127]
	v_mfma_f32_16x16x32_bf16 v[116:119], v[190:193], v[224:227], v[116:119]
	v_mfma_f32_16x16x32_bf16 v[108:111], v[150:153], v[232:235], v[108:111]
	v_mfma_f32_16x16x32_bf16 v[100:103], v[190:193], v[232:235], v[100:103]
	v_mfma_f32_16x16x32_bf16 v[92:95], v[150:153], v[240:243], v[92:95]
	v_mfma_f32_16x16x32_bf16 v[84:87], v[190:193], v[240:243], v[84:87]
	v_mfma_f32_16x16x32_bf16 v[76:79], v[150:153], v[248:251], v[76:79]
	v_mfma_f32_16x16x32_bf16 v[68:71], v[190:193], v[248:251], v[68:71]
	s_setprio 0
	s_setprio 1
	v_mfma_f32_16x16x32_bf16 v[120:123], v[194:197], v[220:223], v[120:123]
	v_mfma_f32_16x16x32_bf16 v[112:115], v[202:205], v[220:223], v[112:115]
	v_mfma_f32_16x16x32_bf16 v[104:107], v[194:197], v[228:231], v[104:107]
	v_mfma_f32_16x16x32_bf16 v[96:99], v[202:205], v[228:231], v[96:99]
	v_mfma_f32_16x16x32_bf16 v[88:91], v[194:197], v[236:239], v[88:91]
	v_mfma_f32_16x16x32_bf16 v[80:83], v[202:205], v[236:239], v[80:83]
	v_mfma_f32_16x16x32_bf16 v[72:75], v[194:197], v[244:247], v[72:75]
	v_mfma_f32_16x16x32_bf16 v[64:67], v[202:205], v[244:247], v[64:67]
	v_mfma_f32_16x16x32_bf16 v[120:123], v[198:201], v[224:227], v[120:123]
	v_mfma_f32_16x16x32_bf16 v[112:115], v[206:209], v[224:227], v[112:115]
	v_mfma_f32_16x16x32_bf16 v[104:107], v[198:201], v[232:235], v[104:107]
	v_mfma_f32_16x16x32_bf16 v[96:99], v[206:209], v[232:235], v[96:99]
	v_mfma_f32_16x16x32_bf16 v[88:91], v[198:201], v[240:243], v[88:91]
	v_mfma_f32_16x16x32_bf16 v[80:83], v[206:209], v[240:243], v[80:83]
	v_mfma_f32_16x16x32_bf16 v[72:75], v[198:201], v[248:251], v[72:75]
	v_mfma_f32_16x16x32_bf16 v[64:67], v[206:209], v[248:251], v[64:67]
	s_setprio 0
	s_barrier
	s_add_i32 s18, s60, s22
	v_lshl_add_u64 v[154:155], v[154:155], 0, s[50:51]
	s_mov_b32 m0, s18
	ds_read_b128 v[220:223], v164 offset:49152
	ds_read_b128 v[224:227], v164 offset:50176
	ds_read_b128 v[228:231], v164 offset:51200
	ds_read_b128 v[232:235], v164 offset:52224
	ds_read_b128 v[236:239], v164 offset:53248
	ds_read_b128 v[240:243], v164 offset:54272
	ds_read_b128 v[244:247], v164 offset:55296
	ds_read_b128 v[248:251], v164 offset:56320
	global_load_lds_dwordx4 v[154:155], off
	s_add_i32 m0, s18, 0x2000
	s_add_u32 s16, s16, 0x40080
	v_lshl_add_u64 v[154:155], v[158:159], 0, s[50:51]
	s_addc_u32 s17, s17, 0
	s_add_i32 s18, s61, s22
	global_load_lds_dwordx4 v[154:155], off
	v_lshl_add_u64 v[154:155], s[16:17], 0, v[132:133]
	s_mov_b32 m0, s18
	s_nop 0
	global_load_lds_dwordx4 v[154:155], off
	v_lshl_add_u64 v[154:155], s[16:17], 0, v[128:129]
	s_add_i32 m0, s18, 0x2000
	s_nop 0
	global_load_lds_dwordx4 v[154:155], off
	v_lshl_add_u64 v[154:155], v[162:163], 0, s[50:51]
	s_mov_b32 m0, s35
	s_nop 0
	global_load_lds_dwordx4 v[154:155], off
	v_lshl_add_u64 v[154:155], v[166:167], 0, s[50:51]
	s_mov_b32 m0, s86
	s_nop 0
	global_load_lds_dwordx4 v[154:155], off
	s_waitcnt vmcnt(8)
	s_waitcnt lgkmcnt(0)
	s_barrier
	s_setprio 1
	s_waitcnt lgkmcnt(0)
	v_mfma_f32_16x16x32_bf16 v[60:63], v[146:149], v[220:223], v[60:63]
	v_mfma_f32_16x16x32_bf16 v[52:55], v[178:181], v[220:223], v[52:55]
	v_mfma_f32_16x16x32_bf16 v[44:47], v[146:149], v[228:231], v[44:47]
	v_mfma_f32_16x16x32_bf16 v[36:39], v[178:181], v[228:231], v[36:39]
	v_mfma_f32_16x16x32_bf16 v[28:31], v[146:149], v[236:239], v[28:31]
	v_mfma_f32_16x16x32_bf16 v[20:23], v[178:181], v[236:239], v[20:23]
	v_mfma_f32_16x16x32_bf16 v[12:15], v[146:149], v[244:247], v[12:15]
	v_mfma_f32_16x16x32_bf16 v[4:7], v[178:181], v[244:247], v[4:7]
	v_mfma_f32_16x16x32_bf16 v[60:63], v[150:153], v[224:227], v[60:63]
	v_mfma_f32_16x16x32_bf16 v[52:55], v[190:193], v[224:227], v[52:55]
	v_mfma_f32_16x16x32_bf16 v[44:47], v[150:153], v[232:235], v[44:47]
	v_mfma_f32_16x16x32_bf16 v[36:39], v[190:193], v[232:235], v[36:39]
	v_mfma_f32_16x16x32_bf16 v[28:31], v[150:153], v[240:243], v[28:31]
	v_mfma_f32_16x16x32_bf16 v[20:23], v[190:193], v[240:243], v[20:23]
	v_mfma_f32_16x16x32_bf16 v[12:15], v[150:153], v[248:251], v[12:15]
	v_mfma_f32_16x16x32_bf16 v[4:7], v[190:193], v[248:251], v[4:7]
	s_setprio 0
	s_setprio 1
	v_mfma_f32_16x16x32_bf16 v[56:59], v[194:197], v[220:223], v[56:59]
	v_mfma_f32_16x16x32_bf16 v[48:51], v[202:205], v[220:223], v[48:51]
	v_mfma_f32_16x16x32_bf16 v[40:43], v[194:197], v[228:231], v[40:43]
	v_mfma_f32_16x16x32_bf16 v[32:35], v[202:205], v[228:231], v[32:35]
	v_mfma_f32_16x16x32_bf16 v[24:27], v[194:197], v[236:239], v[24:27]
	v_mfma_f32_16x16x32_bf16 v[16:19], v[202:205], v[236:239], v[16:19]
	v_mfma_f32_16x16x32_bf16 v[8:11], v[194:197], v[244:247], v[8:11]
	v_mfma_f32_16x16x32_bf16 v[0:3], v[202:205], v[244:247], v[0:3]
	v_mfma_f32_16x16x32_bf16 v[56:59], v[198:201], v[224:227], v[56:59]
	v_mfma_f32_16x16x32_bf16 v[48:51], v[206:209], v[224:227], v[48:51]
	v_mfma_f32_16x16x32_bf16 v[40:43], v[198:201], v[232:235], v[40:43]
	v_mfma_f32_16x16x32_bf16 v[32:35], v[206:209], v[232:235], v[32:35]
	v_mfma_f32_16x16x32_bf16 v[24:27], v[198:201], v[240:243], v[24:27]
	v_mfma_f32_16x16x32_bf16 v[16:19], v[206:209], v[240:243], v[16:19]
	v_mfma_f32_16x16x32_bf16 v[8:11], v[198:201], v[248:251], v[8:11]
	v_mfma_f32_16x16x32_bf16 v[0:3], v[206:209], v[248:251], v[0:3]
	s_add_i32 s59, s59, 2
	s_add_u32 s0, s0, 0x100
	s_addc_u32 s1, s1, 0
	s_add_u32 s57, s57, 0x100
	s_addc_u32 s58, s58, 0
	s_cmp_gt_u32 s59, 13
	s_setprio 0
	s_barrier
	s_cbranch_scc0 .LBB0_1065
	s_and_b64 vcc, exec, s[6:7]
	s_cbranch_vccz .LBB0_1068
	s_barrier

.LBB0_1141:
	s_add_u32 s14, s12, 0x10000
	s_addc_u32 s15, s13, 0
	s_cmp_eq_u32 s90, 40
	s_cselect_b32 s20, s0, s14
	s_cselect_b32 s21, s1, s15
	s_cselect_b32 s18, s10, s58
	s_cselect_b32 s19, s11, s59
	s_add_u32 s16, s20, 0x8000
	s_addc_u32 s17, s21, 0
	s_add_i32 s60, 0, 0x10000
	s_add_i32 s61, 0, 0x14000
	v_add_u32_e32 v140, s60, v196
	v_add_u32_e32 v166, s61, v196
	ds_read_b128 v[120:123], v140
	ds_read_b128 v[124:127], v140 offset:1024
	ds_read_b128 v[128:131], v140 offset:2048
	ds_read_b128 v[140:143], v140 offset:3072
	ds_read_b128 v[144:147], v166
	ds_read_b128 v[158:161], v166 offset:1024
	ds_read_b128 v[162:165], v166 offset:2048
	ds_read_b128 v[178:181], v166 offset:3072
	v_lshl_add_u64 v[166:167], s[12:13], 0, v[154:155]
	s_add_i32 m0, s25, 0xc000
	ds_read_b128 v[190:193], v198
	ds_read_b128 v[200:203], v198 offset:1024
	ds_read_b128 v[204:207], v198 offset:2048
	ds_read_b128 v[220:223], v198 offset:3072
	ds_read_b128 v[224:227], v198 offset:4096
	ds_read_b128 v[228:231], v198 offset:5120
	ds_read_b128 v[232:235], v198 offset:6144
	ds_read_b128 v[236:239], v198 offset:7168
	global_load_lds_dwordx4 v[166:167], off
	v_lshl_add_u64 v[166:167], s[12:13], 0, v[156:157]
	s_add_i32 m0, s25, 0xe000
	s_nop 0
	global_load_lds_dwordx4 v[166:167], off
	s_waitcnt vmcnt(8)
	s_waitcnt lgkmcnt(0)
	s_barrier
	s_setprio 1
	s_waitcnt lgkmcnt(0)
	v_mfma_f32_16x16x32_bf16 v[136:139], v[120:123], v[190:193], v[136:139]
	v_mfma_f32_16x16x32_bf16 v[132:135], v[128:131], v[190:193], v[132:135]
	v_mfma_f32_16x16x32_bf16 v[108:111], v[120:123], v[204:207], v[108:111]
	v_mfma_f32_16x16x32_bf16 v[104:107], v[128:131], v[204:207], v[104:107]
	v_mfma_f32_16x16x32_bf16 v[92:95], v[120:123], v[224:227], v[92:95]
	v_mfma_f32_16x16x32_bf16 v[88:91], v[128:131], v[224:227], v[88:91]
	v_mfma_f32_16x16x32_bf16 v[76:79], v[120:123], v[232:235], v[76:79]
	v_mfma_f32_16x16x32_bf16 v[72:75], v[128:131], v[232:235], v[72:75]
	v_mfma_f32_16x16x32_bf16 v[136:139], v[124:127], v[200:203], v[136:139]
	v_mfma_f32_16x16x32_bf16 v[132:135], v[140:143], v[200:203], v[132:135]
	v_mfma_f32_16x16x32_bf16 v[108:111], v[124:127], v[220:223], v[108:111]
	v_mfma_f32_16x16x32_bf16 v[104:107], v[140:143], v[220:223], v[104:107]
	v_mfma_f32_16x16x32_bf16 v[92:95], v[124:127], v[228:231], v[92:95]
	v_mfma_f32_16x16x32_bf16 v[88:91], v[140:143], v[228:231], v[88:91]
	v_mfma_f32_16x16x32_bf16 v[76:79], v[124:127], v[236:239], v[76:79]
	v_mfma_f32_16x16x32_bf16 v[72:75], v[140:143], v[236:239], v[72:75]
	s_setprio 0
	s_setprio 1
	v_mfma_f32_16x16x32_bf16 v[116:119], v[144:147], v[190:193], v[116:119]
	v_mfma_f32_16x16x32_bf16 v[112:115], v[162:165], v[190:193], v[112:115]
	v_mfma_f32_16x16x32_bf16 v[100:103], v[144:147], v[204:207], v[100:103]
	v_mfma_f32_16x16x32_bf16 v[96:99], v[162:165], v[204:207], v[96:99]
	v_mfma_f32_16x16x32_bf16 v[84:87], v[144:147], v[224:227], v[84:87]
	v_mfma_f32_16x16x32_bf16 v[80:83], v[162:165], v[224:227], v[80:83]
	v_mfma_f32_16x16x32_bf16 v[68:71], v[144:147], v[232:235], v[68:71]
	v_mfma_f32_16x16x32_bf16 v[64:67], v[162:165], v[232:235], v[64:67]
	v_mfma_f32_16x16x32_bf16 v[116:119], v[158:161], v[200:203], v[116:119]
	v_mfma_f32_16x16x32_bf16 v[112:115], v[178:181], v[200:203], v[112:115]
	v_mfma_f32_16x16x32_bf16 v[100:103], v[158:161], v[220:223], v[100:103]
	v_mfma_f32_16x16x32_bf16 v[96:99], v[178:181], v[220:223], v[96:99]
	v_mfma_f32_16x16x32_bf16 v[84:87], v[158:161], v[228:231], v[84:87]
	v_mfma_f32_16x16x32_bf16 v[80:83], v[178:181], v[228:231], v[80:83]
	v_mfma_f32_16x16x32_bf16 v[68:71], v[158:161], v[236:239], v[68:71]
	v_mfma_f32_16x16x32_bf16 v[64:67], v[178:181], v[236:239], v[64:67]
	s_setprio 0
	s_barrier
	s_add_i32 s12, s60, s24
	v_lshl_add_u64 v[166:167], s[18:19], 0, v[168:169]
	s_mov_b32 m0, s12
	ds_read_b128 v[190:193], v198 offset:16384
	ds_read_b128 v[200:203], v198 offset:17408
	ds_read_b128 v[204:207], v198 offset:18432
	ds_read_b128 v[220:223], v198 offset:19456
	ds_read_b128 v[224:227], v198 offset:20480
	ds_read_b128 v[228:231], v198 offset:21504
	ds_read_b128 v[232:235], v198 offset:22528
	ds_read_b128 v[236:239], v198 offset:23552
	global_load_lds_dwordx4 v[166:167], off
	s_add_i32 m0, s12, 0x2000
	s_add_u32 s12, s18, 0xb0000
	v_lshl_add_u64 v[194:195], s[18:19], 0, v[148:149]
	s_addc_u32 s13, s19, 0
	s_add_i32 s60, s61, s24
	global_load_lds_dwordx4 v[194:195], off
	v_lshl_add_u64 v[208:209], s[12:13], 0, v[168:169]
	s_mov_b32 m0, s60
	s_nop 0
	global_load_lds_dwordx4 v[208:209], off
	v_lshl_add_u64 v[208:209], s[12:13], 0, v[148:149]
	s_add_i32 m0, s60, 0x2000
	s_nop 0
	global_load_lds_dwordx4 v[208:209], off
	v_lshl_add_u64 v[208:209], s[20:21], 0, v[152:153]
	s_mov_b32 m0, s25
	s_nop 0
	global_load_lds_dwordx4 v[208:209], off
	v_lshl_add_u64 v[208:209], s[20:21], 0, v[150:151]
	s_mov_b32 m0, s26
	s_nop 0
	global_load_lds_dwordx4 v[208:209], off
	s_waitcnt vmcnt(8)
	s_waitcnt lgkmcnt(0)
	s_barrier
	s_setprio 1
	s_waitcnt lgkmcnt(0)
	v_mfma_f32_16x16x32_bf16 v[60:63], v[120:123], v[190:193], v[60:63]
	v_mfma_f32_16x16x32_bf16 v[56:59], v[128:131], v[190:193], v[56:59]
	v_mfma_f32_16x16x32_bf16 v[44:47], v[120:123], v[204:207], v[44:47]
	v_mfma_f32_16x16x32_bf16 v[40:43], v[128:131], v[204:207], v[40:43]
	v_mfma_f32_16x16x32_bf16 v[28:31], v[120:123], v[224:227], v[28:31]
	v_mfma_f32_16x16x32_bf16 v[24:27], v[128:131], v[224:227], v[24:27]
	v_mfma_f32_16x16x32_bf16 v[12:15], v[120:123], v[232:235], v[12:15]
	v_mfma_f32_16x16x32_bf16 v[8:11], v[128:131], v[232:235], v[8:11]
	v_mfma_f32_16x16x32_bf16 v[60:63], v[124:127], v[200:203], v[60:63]
	v_mfma_f32_16x16x32_bf16 v[56:59], v[140:143], v[200:203], v[56:59]
	v_mfma_f32_16x16x32_bf16 v[44:47], v[124:127], v[220:223], v[44:47]
	v_mfma_f32_16x16x32_bf16 v[40:43], v[140:143], v[220:223], v[40:43]
	v_mfma_f32_16x16x32_bf16 v[28:31], v[124:127], v[228:231], v[28:31]
	v_mfma_f32_16x16x32_bf16 v[24:27], v[140:143], v[228:231], v[24:27]
	v_mfma_f32_16x16x32_bf16 v[12:15], v[124:127], v[236:239], v[12:15]
	v_mfma_f32_16x16x32_bf16 v[8:11], v[140:143], v[236:239], v[8:11]
	s_setprio 0
	s_setprio 1
	v_mfma_f32_16x16x32_bf16 v[52:55], v[144:147], v[190:193], v[52:55]
	v_mfma_f32_16x16x32_bf16 v[48:51], v[162:165], v[190:193], v[48:51]
	v_mfma_f32_16x16x32_bf16 v[36:39], v[144:147], v[204:207], v[36:39]
	v_mfma_f32_16x16x32_bf16 v[32:35], v[162:165], v[204:207], v[32:35]
	v_mfma_f32_16x16x32_bf16 v[20:23], v[144:147], v[224:227], v[20:23]
	v_mfma_f32_16x16x32_bf16 v[16:19], v[162:165], v[224:227], v[16:19]
	v_mfma_f32_16x16x32_bf16 v[4:7], v[144:147], v[232:235], v[4:7]
	v_mfma_f32_16x16x32_bf16 v[0:3], v[162:165], v[232:235], v[0:3]
	v_mfma_f32_16x16x32_bf16 v[52:55], v[158:161], v[200:203], v[52:55]
	v_mfma_f32_16x16x32_bf16 v[48:51], v[178:181], v[200:203], v[48:51]
	v_mfma_f32_16x16x32_bf16 v[36:39], v[158:161], v[220:223], v[36:39]
	v_mfma_f32_16x16x32_bf16 v[32:35], v[178:181], v[220:223], v[32:35]
	v_mfma_f32_16x16x32_bf16 v[20:23], v[158:161], v[228:231], v[20:23]
	v_mfma_f32_16x16x32_bf16 v[16:19], v[178:181], v[228:231], v[16:19]
	v_mfma_f32_16x16x32_bf16 v[4:7], v[158:161], v[236:239], v[4:7]
	v_mfma_f32_16x16x32_bf16 v[0:3], v[178:181], v[236:239], v[0:3]
	s_setprio 0
	s_barrier
	s_add_i32 s60, 0, 0x18000
	s_add_i32 s61, 0, 0x1c000
	v_add_u32_e32 v140, s60, v196
	v_add_u32_e32 v178, s61, v196
	ds_read_b128 v[120:123], v140
	ds_read_b128 v[124:127], v140 offset:1024
	ds_read_b128 v[128:131], v140 offset:2048
	ds_read_b128 v[140:143], v140 offset:3072
	ds_read_b128 v[144:147], v178
	ds_read_b128 v[158:161], v178 offset:1024
	ds_read_b128 v[162:165], v178 offset:2048
	ds_read_b128 v[178:181], v178 offset:3072
	s_add_u32 s12, s20, 0x2000
	s_addc_u32 s13, s21, 0
	s_mov_b32 m0, s27
	v_lshl_add_u64 v[208:209], s[12:13], 0, v[152:153]
	ds_read_b128 v[190:193], v198 offset:32768
	ds_read_b128 v[200:203], v198 offset:33792
	ds_read_b128 v[204:207], v198 offset:34816
	ds_read_b128 v[220:223], v198 offset:35840
	ds_read_b128 v[224:227], v198 offset:36864
	ds_read_b128 v[228:231], v198 offset:37888
	ds_read_b128 v[232:235], v198 offset:38912
	ds_read_b128 v[236:239], v198 offset:39936
	global_load_lds_dwordx4 v[208:209], off
	v_lshl_add_u64 v[208:209], s[12:13], 0, v[150:151]
	s_mov_b32 m0, s34
	s_nop 0
	global_load_lds_dwordx4 v[208:209], off
	s_waitcnt vmcnt(8)
	s_waitcnt lgkmcnt(0)
	s_barrier
	s_setprio 1
	s_waitcnt lgkmcnt(0)
	v_mfma_f32_16x16x32_bf16 v[136:139], v[120:123], v[190:193], v[136:139]
	v_mfma_f32_16x16x32_bf16 v[132:135], v[128:131], v[190:193], v[132:135]
	v_mfma_f32_16x16x32_bf16 v[108:111], v[120:123], v[204:207], v[108:111]
	v_mfma_f32_16x16x32_bf16 v[104:107], v[128:131], v[204:207], v[104:107]
	v_mfma_f32_16x16x32_bf16 v[92:95], v[120:123], v[224:227], v[92:95]
	v_mfma_f32_16x16x32_bf16 v[88:91], v[128:131], v[224:227], v[88:91]
	v_mfma_f32_16x16x32_bf16 v[76:79], v[120:123], v[232:235], v[76:79]
	v_mfma_f32_16x16x32_bf16 v[72:75], v[128:131], v[232:235], v[72:75]
	v_mfma_f32_16x16x32_bf16 v[136:139], v[124:127], v[200:203], v[136:139]
	v_mfma_f32_16x16x32_bf16 v[132:135], v[140:143], v[200:203], v[132:135]
	v_mfma_f32_16x16x32_bf16 v[108:111], v[124:127], v[220:223], v[108:111]
	v_mfma_f32_16x16x32_bf16 v[104:107], v[140:143], v[220:223], v[104:107]
	v_mfma_f32_16x16x32_bf16 v[92:95], v[124:127], v[228:231], v[92:95]
	v_mfma_f32_16x16x32_bf16 v[88:91], v[140:143], v[228:231], v[88:91]
	v_mfma_f32_16x16x32_bf16 v[76:79], v[124:127], v[236:239], v[76:79]
	v_mfma_f32_16x16x32_bf16 v[72:75], v[140:143], v[236:239], v[72:75]
	s_setprio 0
	s_setprio 1
	v_mfma_f32_16x16x32_bf16 v[116:119], v[144:147], v[190:193], v[116:119]
	v_mfma_f32_16x16x32_bf16 v[112:115], v[162:165], v[190:193], v[112:115]
	v_mfma_f32_16x16x32_bf16 v[100:103], v[144:147], v[204:207], v[100:103]
	v_mfma_f32_16x16x32_bf16 v[96:99], v[162:165], v[204:207], v[96:99]
	v_mfma_f32_16x16x32_bf16 v[84:87], v[144:147], v[224:227], v[84:87]
	v_mfma_f32_16x16x32_bf16 v[80:83], v[162:165], v[224:227], v[80:83]
	v_mfma_f32_16x16x32_bf16 v[68:71], v[144:147], v[232:235], v[68:71]
	v_mfma_f32_16x16x32_bf16 v[64:67], v[162:165], v[232:235], v[64:67]
	v_mfma_f32_16x16x32_bf16 v[116:119], v[158:161], v[200:203], v[116:119]
	v_mfma_f32_16x16x32_bf16 v[112:115], v[178:181], v[200:203], v[112:115]
	v_mfma_f32_16x16x32_bf16 v[100:103], v[158:161], v[220:223], v[100:103]
	v_mfma_f32_16x16x32_bf16 v[96:99], v[178:181], v[220:223], v[96:99]
	v_mfma_f32_16x16x32_bf16 v[84:87], v[158:161], v[228:231], v[84:87]
	v_mfma_f32_16x16x32_bf16 v[80:83], v[178:181], v[228:231], v[80:83]
	v_mfma_f32_16x16x32_bf16 v[68:71], v[158:161], v[236:239], v[68:71]
	v_mfma_f32_16x16x32_bf16 v[64:67], v[178:181], v[236:239], v[64:67]
	s_setprio 0
	s_barrier
	s_add_i32 s12, s60, s24
	v_lshl_add_u64 v[166:167], v[166:167], 0, s[50:51]
	s_mov_b32 m0, s12
	ds_read_b128 v[190:193], v198 offset:49152
	ds_read_b128 v[200:203], v198 offset:50176
	ds_read_b128 v[204:207], v198 offset:51200
	ds_read_b128 v[220:223], v198 offset:52224
	ds_read_b128 v[224:227], v198 offset:53248
	ds_read_b128 v[228:231], v198 offset:54272
	ds_read_b128 v[232:235], v198 offset:55296
	ds_read_b128 v[236:239], v198 offset:56320
	global_load_lds_dwordx4 v[166:167], off
	s_add_i32 m0, s12, 0x2000
	s_add_u32 s12, s18, 0xb0080
	v_lshl_add_u64 v[166:167], v[194:195], 0, s[50:51]
	s_addc_u32 s13, s19, 0
	s_add_i32 s18, s61, s24
	global_load_lds_dwordx4 v[166:167], off
	v_lshl_add_u64 v[166:167], s[12:13], 0, v[168:169]
	s_mov_b32 m0, s18
	s_nop 0
	global_load_lds_dwordx4 v[166:167], off
	v_lshl_add_u64 v[166:167], s[12:13], 0, v[148:149]
	s_add_i32 m0, s18, 0x2000
	s_nop 0
	global_load_lds_dwordx4 v[166:167], off
	v_lshl_add_u64 v[166:167], s[16:17], 0, v[152:153]
	s_mov_b32 m0, s86
	s_nop 0
	global_load_lds_dwordx4 v[166:167], off
	v_lshl_add_u64 v[166:167], s[16:17], 0, v[150:151]
	s_mov_b32 m0, s87
	s_nop 0
	global_load_lds_dwordx4 v[166:167], off
	s_waitcnt vmcnt(8)
	s_waitcnt lgkmcnt(0)
	s_barrier
	s_setprio 1
	s_waitcnt lgkmcnt(0)
	v_mfma_f32_16x16x32_bf16 v[60:63], v[120:123], v[190:193], v[60:63]
	v_mfma_f32_16x16x32_bf16 v[56:59], v[128:131], v[190:193], v[56:59]
	v_mfma_f32_16x16x32_bf16 v[44:47], v[120:123], v[204:207], v[44:47]
	v_mfma_f32_16x16x32_bf16 v[40:43], v[128:131], v[204:207], v[40:43]
	v_mfma_f32_16x16x32_bf16 v[28:31], v[120:123], v[224:227], v[28:31]
	v_mfma_f32_16x16x32_bf16 v[24:27], v[128:131], v[224:227], v[24:27]
	v_mfma_f32_16x16x32_bf16 v[12:15], v[120:123], v[232:235], v[12:15]
	v_mfma_f32_16x16x32_bf16 v[8:11], v[128:131], v[232:235], v[8:11]
	v_mfma_f32_16x16x32_bf16 v[60:63], v[124:127], v[200:203], v[60:63]
	v_mfma_f32_16x16x32_bf16 v[56:59], v[140:143], v[200:203], v[56:59]
	v_mfma_f32_16x16x32_bf16 v[44:47], v[124:127], v[220:223], v[44:47]
	v_mfma_f32_16x16x32_bf16 v[40:43], v[140:143], v[220:223], v[40:43]
	v_mfma_f32_16x16x32_bf16 v[28:31], v[124:127], v[228:231], v[28:31]
	v_mfma_f32_16x16x32_bf16 v[24:27], v[140:143], v[228:231], v[24:27]
	v_mfma_f32_16x16x32_bf16 v[12:15], v[124:127], v[236:239], v[12:15]
	v_mfma_f32_16x16x32_bf16 v[8:11], v[140:143], v[236:239], v[8:11]
	s_setprio 0
	s_setprio 1
	v_mfma_f32_16x16x32_bf16 v[52:55], v[144:147], v[190:193], v[52:55]
	v_mfma_f32_16x16x32_bf16 v[48:51], v[162:165], v[190:193], v[48:51]
	v_mfma_f32_16x16x32_bf16 v[36:39], v[144:147], v[204:207], v[36:39]
	v_mfma_f32_16x16x32_bf16 v[32:35], v[162:165], v[204:207], v[32:35]
	v_mfma_f32_16x16x32_bf16 v[20:23], v[144:147], v[224:227], v[20:23]
	v_mfma_f32_16x16x32_bf16 v[16:19], v[162:165], v[224:227], v[16:19]
	v_mfma_f32_16x16x32_bf16 v[4:7], v[144:147], v[232:235], v[4:7]
	v_mfma_f32_16x16x32_bf16 v[0:3], v[162:165], v[232:235], v[0:3]
	v_mfma_f32_16x16x32_bf16 v[52:55], v[158:161], v[200:203], v[52:55]
	v_mfma_f32_16x16x32_bf16 v[48:51], v[178:181], v[200:203], v[48:51]
	v_mfma_f32_16x16x32_bf16 v[36:39], v[158:161], v[220:223], v[36:39]
	v_mfma_f32_16x16x32_bf16 v[32:35], v[178:181], v[220:223], v[32:35]
	v_mfma_f32_16x16x32_bf16 v[20:23], v[158:161], v[228:231], v[20:23]
	v_mfma_f32_16x16x32_bf16 v[16:19], v[178:181], v[228:231], v[16:19]
	v_mfma_f32_16x16x32_bf16 v[4:7], v[158:161], v[236:239], v[4:7]
	v_mfma_f32_16x16x32_bf16 v[0:3], v[178:181], v[236:239], v[0:3]
	s_add_i32 s90, s90, 2
	s_add_u32 s58, s58, 0x100
	s_addc_u32 s59, s59, 0
	s_cmp_gt_u32 s90, 41
	s_mov_b64 s[12:13], s[14:15]
	s_setprio 0
	s_barrier
	s_cbranch_scc0 .LBB0_1141
	s_and_b64 vcc, exec, s[8:9]
	s_cbranch_vccz .LBB0_1144
	s_barrier
